# v21: memKV epilogue per-row scale loads hoisted (8 serialized load+drain round trips -> 1) in both K and V paths; DN K-loop MFMA runs re-aligned to 8 bytes
# baseline (speedup 1.0000x reference)
; #define PG8_STAGE(bufoff, gbase, voff) do { _Pragma("unroll") for (int _i = 0; _i < 2; ++_i) \
;         __builtin_amdgcn_global_load_lds((const unsigned*)((const char*)(gbase) + (voff)[_i]), (PG8_LAS unsigned*)(lds + (bufoff) + ldsw + _i * 8192), 16, 0, 0); } while (0)
; #define PG8_LDA(dst, b, h) do { _Pragma("unroll") for (int m = 0; m < 4; ++m) _Pragma("unroll") for (int k = 0; k < 2; ++k) dst[m][k] = *(const PG8_LAS bf16x8*)(lds + PG8_SA(b, h) + aoff + m * 2048 + k * 1024); } while (0)
; #define PG8_LDB(dst, b, h) do { _Pragma("unroll") for (int n = 0; n < 2; ++n) _Pragma("unroll") for (int k = 0; k < 2; ++k) dst[n][k] = *(const PG8_LAS bf16x8*)(lds + PG8_SB(b, h) + boff + n * 2048 + k * 1024); } while (0)
; #define PG8_MMA(ai, bj, At, Bt) do { __builtin_amdgcn_s_setprio(1); _Pragma("unroll") for (int m = 0; m < 4; ++m) _Pragma("unroll") for (int n = 0; n < 2; ++n) _Pragma("unroll") for (int k = 0; k < 2; ++k) \
;         acc[ai][bj][m][n] = __builtin_amdgcn_mfma_f32_16x16x32_bf16(Bt[n][k], At[m][k], acc[ai][bj][m][n], 0, 0, 0); __builtin_amdgcn_s_setprio(0); } while (0)
; #define PG8_WAIT_V(n) asm volatile("s_waitcnt vmcnt(" #n ")" ::: "memory")
; #define PG8_WAIT_L(n) asm volatile("s_waitcnt lgkmcnt(" #n ")" ::: "memory")
; #define PG8_BAR __builtin_amdgcn_s_barrier()
; #define PG8_SCHED __builtin_amdgcn_sched_barrier(0)
; template <class Epi, class Sched, bool ALIGN_EPI = false, bool SP2 = false>
; __device__ __forceinline__ void gemm_phase(PG8_LAS unsigned char* lds, const Gemm g, const Sched& S, const Epi& E) {
;     ...
;             const bool last = (t == nt - 2);
;             const char* a1 = cA + (size_t)(t + 1) * kstep;
;             const char* a2 = last ? nA : cA + (size_t)(t + 2) * kstep; const char* b2 = last ? nB : cB + (size_t)(t + 2) * kstep;
;             const char* a3 = a2 + kstep; const char* b3 = b2 + kstep;
;             if (last && has_next) S.a_ready(nxt);
;             if constexpr (SP2) {
;             PG8_LDB(B0, 0, 0); PG8_LDB(B1, 0, 1); PG8_SCHED; PG8_LDA(At, 0, 0); PG8_STAGE(PG8_SA(1, 1), a1 + hstep, voffA);
;             PG8_WAIT_V(8); PG8_WAIT_L(0); PG8_BAR; PG8_MMA(0, 0, At, B0); PG8_MMA(0, 1, At, B1); PG8_BAR; PG8_SCHED;
;             PG8_LDA(At, 0, 1); PG8_STAGE(PG8_SB(0, 0), b2, voffB); PG8_STAGE(PG8_SB(0, 1), b2 + hstep, voffB); PG8_STAGE(PG8_SA(0, 0), a2, voffA);
.LBB0_461:
	s_add_u32 s0, s22, 0x100
	s_addc_u32 s1, s23, 0
	s_cmp_eq_u32 s50, 40
	s_cselect_b32 s27, s19, s1
	s_cselect_b32 s26, s18, s0
	s_cselect_b32 s25, s21, s5
	s_cselect_b32 s24, s20, s4
	s_add_i32 s6, 0, 0x10000
	s_add_i32 s51, 0, 0x14000
	v_add_u32_e32 v140, s6, v228
	v_add_u32_e32 v156, s51, v228
	ds_read_b128 v[128:131], v140
	ds_read_b128 v[132:135], v140 offset:1024
	ds_read_b128 v[136:139], v140 offset:2048
	ds_read_b128 v[140:143], v140 offset:3072
	ds_read_b128 v[144:147], v156
	ds_read_b128 v[148:151], v156 offset:1024
	ds_read_b128 v[152:155], v156 offset:2048
	ds_read_b128 v[156:159], v156 offset:3072
	s_add_u32 s98, s22, 0xb0080
	s_addc_u32 s99, s23, 0
	s_add_i32 m0, s30, 0xc000
	ds_read_b128 v[160:163], v230
	ds_read_b128 v[164:167], v230 offset:1024
	ds_read_b128 v[168:171], v230 offset:2048
	ds_read_b128 v[172:175], v230 offset:3072
	ds_read_b128 v[176:179], v230 offset:4096
	ds_read_b128 v[180:183], v230 offset:5120
	ds_read_b128 v[204:207], v230 offset:6144
	ds_read_b128 v[208:211], v230 offset:7168
	ds_read_b128 v[212:215], v249
	ds_read_b128 v[232:235], v249 offset:1024
	global_load_lds_dwordx4 v198, s[98:99]
	s_add_i32 m0, s30, 0xe000
	s_nop 0
	global_load_lds_dwordx4 v196, s[98:99]
	s_nop 0
	s_waitcnt vmcnt(9)
	s_waitcnt lgkmcnt(0)
	s_barrier
	s_setprio 1
	s_waitcnt lgkmcnt(0)
	v_mfma_f32_16x16x32_bf16 v[124:127], v[128:131], v[160:163], v[124:127]
	v_mfma_f32_16x16x32_bf16 v[120:123], v[136:139], v[160:163], v[120:123]
	v_mfma_f32_16x16x32_bf16 v[108:111], v[128:131], v[168:171], v[108:111]
	v_mfma_f32_16x16x32_bf16 v[104:107], v[136:139], v[168:171], v[104:107]
	v_mfma_f32_16x16x32_bf16 v[92:95], v[128:131], v[176:179], v[92:95]
	v_mfma_f32_16x16x32_bf16 v[88:91], v[136:139], v[176:179], v[88:91]
	v_mfma_f32_16x16x32_bf16 v[76:79], v[128:131], v[204:207], v[76:79]
	v_mfma_f32_16x16x32_bf16 v[72:75], v[136:139], v[204:207], v[72:75]
	v_mfma_f32_16x16x32_bf16 v[124:127], v[132:135], v[164:167], v[124:127]
	v_mfma_f32_16x16x32_bf16 v[120:123], v[140:143], v[164:167], v[120:123]
	v_mfma_f32_16x16x32_bf16 v[108:111], v[132:135], v[172:175], v[108:111]
	v_mfma_f32_16x16x32_bf16 v[104:107], v[140:143], v[172:175], v[104:107]
	v_mfma_f32_16x16x32_bf16 v[92:95], v[132:135], v[180:183], v[92:95]
	v_mfma_f32_16x16x32_bf16 v[88:91], v[140:143], v[180:183], v[88:91]
	v_mfma_f32_16x16x32_bf16 v[76:79], v[132:135], v[208:211], v[76:79]
	v_mfma_f32_16x16x32_bf16 v[72:75], v[140:143], v[208:211], v[72:75]
	s_setprio 0
	s_setprio 1
	v_mfma_f32_16x16x32_bf16 v[116:119], v[144:147], v[160:163], v[116:119]
	v_mfma_f32_16x16x32_bf16 v[112:115], v[152:155], v[160:163], v[112:115]
	v_mfma_f32_16x16x32_bf16 v[100:103], v[144:147], v[168:171], v[100:103]
	v_mfma_f32_16x16x32_bf16 v[96:99], v[152:155], v[168:171], v[96:99]
	v_mfma_f32_16x16x32_bf16 v[84:87], v[144:147], v[176:179], v[84:87]
	v_mfma_f32_16x16x32_bf16 v[80:83], v[152:155], v[176:179], v[80:83]
	v_mfma_f32_16x16x32_bf16 v[68:71], v[144:147], v[204:207], v[68:71]
	v_mfma_f32_16x16x32_bf16 v[64:67], v[152:155], v[204:207], v[64:67]
	v_mfma_f32_16x16x32_bf16 v[116:119], v[148:151], v[164:167], v[116:119]
	v_mfma_f32_16x16x32_bf16 v[112:115], v[156:159], v[164:167], v[112:115]
	v_mfma_f32_16x16x32_bf16 v[100:103], v[148:151], v[172:175], v[100:103]
	v_mfma_f32_16x16x32_bf16 v[96:99], v[156:159], v[172:175], v[96:99]
	v_mfma_f32_16x16x32_bf16 v[84:87], v[148:151], v[180:183], v[84:87]
	v_mfma_f32_16x16x32_bf16 v[80:83], v[156:159], v[180:183], v[80:83]
	v_mfma_f32_16x16x32_bf16 v[68:71], v[148:151], v[208:211], v[68:71]
	v_mfma_f32_16x16x32_bf16 v[64:67], v[156:159], v[208:211], v[64:67]
	v_mfma_f32_16x16x32_bf16 v[236:239], v[128:131], v[212:215], v[236:239]
	v_mfma_f32_16x16x32_bf16 v[240:243], v[136:139], v[212:215], v[240:243]
	v_mfma_f32_16x16x32_bf16 v[244:247], v[144:147], v[212:215], v[244:247]
	v_mfma_f32_16x16x32_bf16 v[200:203], v[152:155], v[212:215], v[200:203]
	v_mfma_f32_16x16x32_bf16 v[236:239], v[132:135], v[232:235], v[236:239]
	v_mfma_f32_16x16x32_bf16 v[240:243], v[140:143], v[232:235], v[240:243]
	v_mfma_f32_16x16x32_bf16 v[244:247], v[148:151], v[232:235], v[244:247]
	v_mfma_f32_16x16x32_bf16 v[200:203], v[156:159], v[232:235], v[200:203]
	s_setprio 0
	s_barrier
	s_add_i32 s6, s6, s29
	s_mov_b32 m0, s6
	ds_read_b128 v[160:163], v230 offset:16384
	ds_read_b128 v[164:167], v230 offset:17408
	ds_read_b128 v[168:171], v230 offset:18432
	ds_read_b128 v[172:175], v230 offset:19456
	ds_read_b128 v[176:179], v230 offset:20480
	ds_read_b128 v[180:183], v230 offset:21504
	ds_read_b128 v[204:207], v230 offset:22528
	ds_read_b128 v[208:211], v230 offset:23552
	global_load_lds_dwordx4 v184, s[24:25]
	s_add_i32 m0, s6, 0x2000
	s_add_u32 s22, s24, 0xb0000
	s_addc_u32 s23, s25, 0
	s_add_i32 s6, s51, s29
	global_load_lds_dwordx4 v194, s[24:25]
	s_mov_b32 m0, s6
	s_nop 0
	global_load_lds_dwordx4 v184, s[22:23]
	s_add_i32 m0, s6, 0x2000
	s_nop 0
	global_load_lds_dwordx4 v194, s[22:23]
	s_mov_b32 m0, s30
	s_nop 0
	global_load_lds_dwordx4 v198, s[26:27]
	s_mov_b32 m0, s31
	s_nop 0
	global_load_lds_dwordx4 v196, s[26:27]
	s_and_b32 m0, s30, 0xc00
	s_add_i32 m0, m0, 0x20800
	s_nop 0
	global_load_lds_dwordx4 v248, s[26:27]
	s_nop 0
	s_waitcnt vmcnt(9)
	s_waitcnt lgkmcnt(0)
	s_barrier
; #define PG8_STAGE(bufoff, gbase, voff) do { _Pragma("unroll") for (int _i = 0; _i < 2; ++_i) \
;         __builtin_amdgcn_global_load_lds((const unsigned*)((const char*)(gbase) + (voff)[_i]), (PG8_LAS unsigned*)(lds + (bufoff) + ldsw + _i * 8192), 16, 0, 0); } while (0)
; #define PG8_LDA(dst, b, h) do { _Pragma("unroll") for (int m = 0; m < 4; ++m) _Pragma("unroll") for (int k = 0; k < 2; ++k) dst[m][k] = *(const PG8_LAS bf16x8*)(lds + PG8_SA(b, h) + aoff + m * 2048 + k * 1024); } while (0)
; #define PG8_LDB(dst, b, h) do { _Pragma("unroll") for (int n = 0; n < 2; ++n) _Pragma("unroll") for (int k = 0; k < 2; ++k) dst[n][k] = *(const PG8_LAS bf16x8*)(lds + PG8_SB(b, h) + boff + n * 2048 + k * 1024); } while (0)
; #define PG8_MMA(ai, bj, At, Bt) do { __builtin_amdgcn_s_setprio(1); _Pragma("unroll") for (int m = 0; m < 4; ++m) _Pragma("unroll") for (int n = 0; n < 2; ++n) _Pragma("unroll") for (int k = 0; k < 2; ++k) \
;         acc[ai][bj][m][n] = __builtin_amdgcn_mfma_f32_16x16x32_bf16(Bt[n][k], At[m][k], acc[ai][bj][m][n], 0, 0, 0); __builtin_amdgcn_s_setprio(0); } while (0)
; #define PG8_WAIT_V(n) asm volatile("s_waitcnt vmcnt(" #n ")" ::: "memory")
; #define PG8_WAIT_L(n) asm volatile("s_waitcnt lgkmcnt(" #n ")" ::: "memory")
; #define PG8_BAR __builtin_amdgcn_s_barrier()
; #define PG8_SCHED __builtin_amdgcn_sched_barrier(0)
; template <class Epi, class Sched, bool ALIGN_EPI = false, bool SP2 = false>
; __device__ __forceinline__ void gemm_phase(PG8_LAS unsigned char* lds, const Gemm g, const Sched& S, const Epi& E) {
;     ...
;             PG8_WAIT_V(8); PG8_WAIT_L(0); PG8_BAR; PG8_MMA(1, 0, At, B0); PG8_MMA(1, 1, At, B1); PG8_BAR; PG8_SCHED;
;             PG8_LDB(B0, 1, 0); PG8_LDB(B1, 1, 1); PG8_SCHED; PG8_LDA(At, 1, 0); PG8_STAGE(PG8_SA(0, 1), a2 + hstep, voffA);
;             PG8_WAIT_V(8); PG8_WAIT_L(0); PG8_BAR; PG8_MMA(0, 0, At, B0); PG8_MMA(0, 1, At, B1); PG8_BAR; PG8_SCHED;
	s_setprio 1
	s_waitcnt lgkmcnt(0)
	v_mfma_f32_16x16x32_bf16 v[60:63], v[128:131], v[160:163], v[60:63]
	v_mfma_f32_16x16x32_bf16 v[56:59], v[136:139], v[160:163], v[56:59]
	v_mfma_f32_16x16x32_bf16 v[44:47], v[128:131], v[168:171], v[44:47]
	v_mfma_f32_16x16x32_bf16 v[40:43], v[136:139], v[168:171], v[40:43]
	v_mfma_f32_16x16x32_bf16 v[28:31], v[128:131], v[176:179], v[28:31]
	v_mfma_f32_16x16x32_bf16 v[24:27], v[136:139], v[176:179], v[24:27]
	v_mfma_f32_16x16x32_bf16 v[12:15], v[128:131], v[204:207], v[12:15]
	v_mfma_f32_16x16x32_bf16 v[8:11], v[136:139], v[204:207], v[8:11]
	v_mfma_f32_16x16x32_bf16 v[60:63], v[132:135], v[164:167], v[60:63]
	v_mfma_f32_16x16x32_bf16 v[56:59], v[140:143], v[164:167], v[56:59]
	v_mfma_f32_16x16x32_bf16 v[44:47], v[132:135], v[172:175], v[44:47]
	v_mfma_f32_16x16x32_bf16 v[40:43], v[140:143], v[172:175], v[40:43]
	v_mfma_f32_16x16x32_bf16 v[28:31], v[132:135], v[180:183], v[28:31]
	v_mfma_f32_16x16x32_bf16 v[24:27], v[140:143], v[180:183], v[24:27]
	v_mfma_f32_16x16x32_bf16 v[12:15], v[132:135], v[208:211], v[12:15]
	v_mfma_f32_16x16x32_bf16 v[8:11], v[140:143], v[208:211], v[8:11]
	s_setprio 0
	s_setprio 1
	v_mfma_f32_16x16x32_bf16 v[52:55], v[144:147], v[160:163], v[52:55]
	v_mfma_f32_16x16x32_bf16 v[48:51], v[152:155], v[160:163], v[48:51]
	v_mfma_f32_16x16x32_bf16 v[36:39], v[144:147], v[168:171], v[36:39]
	v_mfma_f32_16x16x32_bf16 v[32:35], v[152:155], v[168:171], v[32:35]
	v_mfma_f32_16x16x32_bf16 v[20:23], v[144:147], v[176:179], v[20:23]
	v_mfma_f32_16x16x32_bf16 v[16:19], v[152:155], v[176:179], v[16:19]
	v_mfma_f32_16x16x32_bf16 v[4:7], v[144:147], v[204:207], v[4:7]
	v_mfma_f32_16x16x32_bf16 v[0:3], v[152:155], v[204:207], v[0:3]
	v_mfma_f32_16x16x32_bf16 v[52:55], v[148:151], v[164:167], v[52:55]
	v_mfma_f32_16x16x32_bf16 v[48:51], v[156:159], v[164:167], v[48:51]
	v_mfma_f32_16x16x32_bf16 v[36:39], v[148:151], v[172:175], v[36:39]
	v_mfma_f32_16x16x32_bf16 v[32:35], v[156:159], v[172:175], v[32:35]
	v_mfma_f32_16x16x32_bf16 v[20:23], v[148:151], v[180:183], v[20:23]
	v_mfma_f32_16x16x32_bf16 v[16:19], v[156:159], v[180:183], v[16:19]
	v_mfma_f32_16x16x32_bf16 v[4:7], v[148:151], v[208:211], v[4:7]
	v_mfma_f32_16x16x32_bf16 v[0:3], v[156:159], v[208:211], v[0:3]
	s_setprio 0
	s_barrier
	s_add_i32 s6, 0, 0x18000
	s_add_i32 s51, 0, 0x1c000
	v_add_u32_e32 v140, s6, v228
	v_add_u32_e32 v156, s51, v228
	ds_read_b128 v[128:131], v140
	ds_read_b128 v[132:135], v140 offset:1024
	ds_read_b128 v[136:139], v140 offset:2048
	ds_read_b128 v[140:143], v140 offset:3072
	ds_read_b128 v[144:147], v156
	ds_read_b128 v[148:151], v156 offset:1024
	ds_read_b128 v[152:155], v156 offset:2048
	ds_read_b128 v[156:159], v156 offset:3072
	s_add_u32 s22, s26, 0xb0000
	s_addc_u32 s23, s27, 0
	s_mov_b32 m0, s34
	ds_read_b128 v[160:163], v230 offset:32768
	ds_read_b128 v[164:167], v230 offset:33792
	ds_read_b128 v[168:171], v230 offset:34816
	ds_read_b128 v[172:175], v230 offset:35840
	ds_read_b128 v[176:179], v230 offset:36864
	ds_read_b128 v[180:183], v230 offset:37888
	ds_read_b128 v[204:207], v230 offset:38912
	ds_read_b128 v[208:211], v230 offset:39936
	ds_read_b128 v[212:215], v249 offset:4096
	ds_read_b128 v[232:235], v249 offset:5120
	global_load_lds_dwordx4 v198, s[22:23]
	s_mov_b32 m0, s40
	s_nop 0
	global_load_lds_dwordx4 v196, s[22:23]
	s_nop 0
	s_waitcnt vmcnt(9)
	s_waitcnt lgkmcnt(0)
	s_barrier
; #define PG8_STAGE(bufoff, gbase, voff) do { _Pragma("unroll") for (int _i = 0; _i < 2; ++_i) \
;         __builtin_amdgcn_global_load_lds((const unsigned*)((const char*)(gbase) + (voff)[_i]), (PG8_LAS unsigned*)(lds + (bufoff) + ldsw + _i * 8192), 16, 0, 0); } while (0)
; #define PG8_LDA(dst, b, h) do { _Pragma("unroll") for (int m = 0; m < 4; ++m) _Pragma("unroll") for (int k = 0; k < 2; ++k) dst[m][k] = *(const PG8_LAS bf16x8*)(lds + PG8_SA(b, h) + aoff + m * 2048 + k * 1024); } while (0)
; #define PG8_MMA(ai, bj, At, Bt) do { __builtin_amdgcn_s_setprio(1); _Pragma("unroll") for (int m = 0; m < 4; ++m) _Pragma("unroll") for (int n = 0; n < 2; ++n) _Pragma("unroll") for (int k = 0; k < 2; ++k) \
;         acc[ai][bj][m][n] = __builtin_amdgcn_mfma_f32_16x16x32_bf16(Bt[n][k], At[m][k], acc[ai][bj][m][n], 0, 0, 0); __builtin_amdgcn_s_setprio(0); } while (0)
; #define PG8_WAIT_V(n) asm volatile("s_waitcnt vmcnt(" #n ")" ::: "memory")
; #define PG8_WAIT_L(n) asm volatile("s_waitcnt lgkmcnt(" #n ")" ::: "memory")
; #define PG8_BAR __builtin_amdgcn_s_barrier()
; #define PG8_SCHED __builtin_amdgcn_sched_barrier(0)
; template <class Epi, class Sched, bool ALIGN_EPI = false, bool SP2 = false>
; __device__ __forceinline__ void gemm_phase(PG8_LAS unsigned char* lds, const Gemm g, const Sched& S, const Epi& E) {
;     ...
;             PG8_LDA(At, 1, 1); PG8_STAGE(PG8_SB(1, 0), b3, voffB); PG8_STAGE(PG8_SB(1, 1), b3 + hstep, voffB); PG8_STAGE(PG8_SA(1, 0), a3, voffA);
;             PG8_WAIT_V(8); PG8_WAIT_L(0); PG8_BAR; PG8_MMA(1, 0, At, B0); PG8_MMA(1, 1, At, B1); PG8_BAR; PG8_SCHED;
; __device__ __forceinline__ void small_gemm_res(LAS unsigned char* lds, const bf16* A, const bf16* Bt, int K, const float* base_s, float* out, bf16* AB, float* PS, int sm, int sn, int tid_in) {
;     ...
;     f32x4 bv[2][2];
; #pragma unroll
;     for (int m_ = 0; m_ < 2; ++m_)
; #pragma unroll
;         for (int n = 0; n < 2; ++n) bv[m_][n] = *(const f32x4*)(base_s + (size_t)(row0 + wr * 32 + m_ * 16 + fr - MP) * D + col0 + wc * 32 + n * 16 + 4 * fq);
	s_setprio 1
	s_waitcnt lgkmcnt(0)
	v_mfma_f32_16x16x32_bf16 v[124:127], v[128:131], v[160:163], v[124:127]
	v_mfma_f32_16x16x32_bf16 v[120:123], v[136:139], v[160:163], v[120:123]
	v_mfma_f32_16x16x32_bf16 v[108:111], v[128:131], v[168:171], v[108:111]
	v_mfma_f32_16x16x32_bf16 v[104:107], v[136:139], v[168:171], v[104:107]
	v_mfma_f32_16x16x32_bf16 v[92:95], v[128:131], v[176:179], v[92:95]
	v_mfma_f32_16x16x32_bf16 v[88:91], v[136:139], v[176:179], v[88:91]
	v_mfma_f32_16x16x32_bf16 v[76:79], v[128:131], v[204:207], v[76:79]
	v_mfma_f32_16x16x32_bf16 v[72:75], v[136:139], v[204:207], v[72:75]
	v_mfma_f32_16x16x32_bf16 v[124:127], v[132:135], v[164:167], v[124:127]
	v_mfma_f32_16x16x32_bf16 v[120:123], v[140:143], v[164:167], v[120:123]
	v_mfma_f32_16x16x32_bf16 v[108:111], v[132:135], v[172:175], v[108:111]
	v_mfma_f32_16x16x32_bf16 v[104:107], v[140:143], v[172:175], v[104:107]
	v_mfma_f32_16x16x32_bf16 v[92:95], v[132:135], v[180:183], v[92:95]
	v_mfma_f32_16x16x32_bf16 v[88:91], v[140:143], v[180:183], v[88:91]
	v_mfma_f32_16x16x32_bf16 v[76:79], v[132:135], v[208:211], v[76:79]
	v_mfma_f32_16x16x32_bf16 v[72:75], v[140:143], v[208:211], v[72:75]
	s_setprio 0
	s_setprio 1
	v_mfma_f32_16x16x32_bf16 v[116:119], v[144:147], v[160:163], v[116:119]
	v_mfma_f32_16x16x32_bf16 v[112:115], v[152:155], v[160:163], v[112:115]
	v_mfma_f32_16x16x32_bf16 v[100:103], v[144:147], v[168:171], v[100:103]
	v_mfma_f32_16x16x32_bf16 v[96:99], v[152:155], v[168:171], v[96:99]
	v_mfma_f32_16x16x32_bf16 v[84:87], v[144:147], v[176:179], v[84:87]
	v_mfma_f32_16x16x32_bf16 v[80:83], v[152:155], v[176:179], v[80:83]
	v_mfma_f32_16x16x32_bf16 v[68:71], v[144:147], v[204:207], v[68:71]
	v_mfma_f32_16x16x32_bf16 v[64:67], v[152:155], v[204:207], v[64:67]
	v_mfma_f32_16x16x32_bf16 v[116:119], v[148:151], v[164:167], v[116:119]
	v_mfma_f32_16x16x32_bf16 v[112:115], v[156:159], v[164:167], v[112:115]
	v_mfma_f32_16x16x32_bf16 v[100:103], v[148:151], v[172:175], v[100:103]
	v_mfma_f32_16x16x32_bf16 v[96:99], v[156:159], v[172:175], v[96:99]
	v_mfma_f32_16x16x32_bf16 v[84:87], v[148:151], v[180:183], v[84:87]
	v_mfma_f32_16x16x32_bf16 v[80:83], v[156:159], v[180:183], v[80:83]
	v_mfma_f32_16x16x32_bf16 v[68:71], v[148:151], v[208:211], v[68:71]
	v_mfma_f32_16x16x32_bf16 v[64:67], v[156:159], v[208:211], v[64:67]
	v_mfma_f32_16x16x32_bf16 v[236:239], v[128:131], v[212:215], v[236:239]
	v_mfma_f32_16x16x32_bf16 v[240:243], v[136:139], v[212:215], v[240:243]
	v_mfma_f32_16x16x32_bf16 v[244:247], v[144:147], v[212:215], v[244:247]
	v_mfma_f32_16x16x32_bf16 v[200:203], v[152:155], v[212:215], v[200:203]
	v_mfma_f32_16x16x32_bf16 v[236:239], v[132:135], v[232:235], v[236:239]
	v_mfma_f32_16x16x32_bf16 v[240:243], v[140:143], v[232:235], v[240:243]
	v_mfma_f32_16x16x32_bf16 v[244:247], v[148:151], v[232:235], v[244:247]
	v_mfma_f32_16x16x32_bf16 v[200:203], v[156:159], v[232:235], v[200:203]
	s_setprio 0
	s_barrier
	s_add_i32 s22, s6, s29
	s_add_u32 s98, s24, 0x80
	s_addc_u32 s99, s25, 0
	s_mov_b32 m0, s22
	ds_read_b128 v[160:163], v230 offset:49152
	ds_read_b128 v[164:167], v230 offset:50176
	ds_read_b128 v[168:171], v230 offset:51200
	ds_read_b128 v[172:175], v230 offset:52224
	ds_read_b128 v[176:179], v230 offset:53248
	ds_read_b128 v[180:183], v230 offset:54272
	ds_read_b128 v[204:207], v230 offset:55296
	ds_read_b128 v[208:211], v230 offset:56320
	global_load_lds_dwordx4 v184, s[98:99]
	s_add_i32 m0, s22, 0x2000
	s_add_u32 s100, s24, 0xb0080
	s_addc_u32 s101, s25, 0
	s_add_i32 s22, s51, s29
	global_load_lds_dwordx4 v194, s[98:99]
	s_mov_b32 m0, s22
	s_add_u32 s98, s26, 0x80
	s_addc_u32 s99, s27, 0
	global_load_lds_dwordx4 v184, s[100:101]
	s_add_i32 m0, s22, 0x2000
	s_nop 0
	global_load_lds_dwordx4 v194, s[100:101]
	s_mov_b32 m0, s41
	s_nop 0
	global_load_lds_dwordx4 v198, s[98:99]
	s_mov_b32 m0, s42
	s_nop 0
	global_load_lds_dwordx4 v196, s[98:99]
	s_and_b32 m0, s30, 0xc00
	s_add_i32 m0, m0, 0x21800
	s_nop 0
	global_load_lds_dwordx4 v248, s[98:99]
	s_waitcnt vmcnt(9)
	s_waitcnt lgkmcnt(0)
	s_barrier
	s_setprio 1
	s_waitcnt lgkmcnt(0)
	v_mfma_f32_16x16x32_bf16 v[60:63], v[128:131], v[160:163], v[60:63]
	v_mfma_f32_16x16x32_bf16 v[56:59], v[136:139], v[160:163], v[56:59]
	v_mfma_f32_16x16x32_bf16 v[44:47], v[128:131], v[168:171], v[44:47]
	v_mfma_f32_16x16x32_bf16 v[40:43], v[136:139], v[168:171], v[40:43]
	v_mfma_f32_16x16x32_bf16 v[28:31], v[128:131], v[176:179], v[28:31]
	v_mfma_f32_16x16x32_bf16 v[24:27], v[136:139], v[176:179], v[24:27]
	v_mfma_f32_16x16x32_bf16 v[12:15], v[128:131], v[204:207], v[12:15]
	v_mfma_f32_16x16x32_bf16 v[8:11], v[136:139], v[204:207], v[8:11]
	v_mfma_f32_16x16x32_bf16 v[60:63], v[132:135], v[164:167], v[60:63]
	v_mfma_f32_16x16x32_bf16 v[56:59], v[140:143], v[164:167], v[56:59]
	v_mfma_f32_16x16x32_bf16 v[44:47], v[132:135], v[172:175], v[44:47]
	v_mfma_f32_16x16x32_bf16 v[40:43], v[140:143], v[172:175], v[40:43]
	v_mfma_f32_16x16x32_bf16 v[28:31], v[132:135], v[180:183], v[28:31]
	v_mfma_f32_16x16x32_bf16 v[24:27], v[140:143], v[180:183], v[24:27]
	v_mfma_f32_16x16x32_bf16 v[12:15], v[132:135], v[208:211], v[12:15]
	v_mfma_f32_16x16x32_bf16 v[8:11], v[140:143], v[208:211], v[8:11]
	s_setprio 0
	s_cmp_eq_u32 s50, 40
	s_cbranch_scc0 .Lxr_skip_461
	s_mul_i32 s98, s48, 0x120
	s_addk_i32 s98, 0x100
	v_and_b32_e32 v190, 15, v227
	v_lshrrev_b32_e32 v191, 6, v227
	v_lshl_add_u32 v190, v191, 4, v190
	v_add_u32_e32 v190, s98, v190
	v_mov_b32_e32 v191, 0
	v_lshlrev_b64 v[190:191], 12, v[190:191]
	v_lshl_add_u64 v[190:191], s[74:75], 0, v[190:191]
	v_lshl_or_b32 v217, s49, 8, v229
	v_lshlrev_b32_e32 v217, 2, v217
	v_add_co_u32_e32 v190, vcc, v190, v217
	s_nop 1
	v_addc_co_u32_e32 v191, vcc, 0, v191, vcc
	global_load_dwordx4 v[128:131], v[190:191], off
	global_load_dwordx4 v[132:135], v[190:191], off offset:16
	global_load_dwordx4 v[136:139], v[190:191], off offset:512
	global_load_dwordx4 v[140:143], v[190:191], off offset:528

; #define PG8_STAGE(bufoff, gbase, voff) do { _Pragma("unroll") for (int _i = 0; _i < 2; ++_i) \
;         __builtin_amdgcn_global_load_lds((const unsigned*)((const char*)(gbase) + (voff)[_i]), (PG8_LAS unsigned*)(lds + (bufoff) + ldsw + _i * 8192), 16, 0, 0); } while (0)
; #define PG8_LDA(dst, b, h) do { _Pragma("unroll") for (int m = 0; m < 4; ++m) _Pragma("unroll") for (int k = 0; k < 2; ++k) dst[m][k] = *(const PG8_LAS bf16x8*)(lds + PG8_SA(b, h) + aoff + m * 2048 + k * 1024); } while (0)
; #define PG8_LDB(dst, b, h) do { _Pragma("unroll") for (int n = 0; n < 2; ++n) _Pragma("unroll") for (int k = 0; k < 2; ++k) dst[n][k] = *(const PG8_LAS bf16x8*)(lds + PG8_SB(b, h) + boff + n * 2048 + k * 1024); } while (0)
; #define PG8_MMA(ai, bj, At, Bt) do { __builtin_amdgcn_s_setprio(1); _Pragma("unroll") for (int m = 0; m < 4; ++m) _Pragma("unroll") for (int n = 0; n < 2; ++n) _Pragma("unroll") for (int k = 0; k < 2; ++k) \
;         acc[ai][bj][m][n] = __builtin_amdgcn_mfma_f32_16x16x32_bf16(Bt[n][k], At[m][k], acc[ai][bj][m][n], 0, 0, 0); __builtin_amdgcn_s_setprio(0); } while (0)
; #define PG8_WAIT_V(n) asm volatile("s_waitcnt vmcnt(" #n ")" ::: "memory")
; #define PG8_WAIT_L(n) asm volatile("s_waitcnt lgkmcnt(" #n ")" ::: "memory")
; #define PG8_BAR __builtin_amdgcn_s_barrier()
; #define PG8_SCHED __builtin_amdgcn_sched_barrier(0)
; template <class Epi, class Sched, bool ALIGN_EPI = false, bool SP2 = false>
; __device__ __forceinline__ void gemm_phase(PG8_LAS unsigned char* lds, const Gemm g, const Sched& S, const Epi& E) {
;     ...
;             const bool last = (t == nt - 2);
;             const char* a1 = cA + (size_t)(t + 1) * kstep;
;             const char* a2 = last ? nA : cA + (size_t)(t + 2) * kstep; const char* b2 = last ? nB : cB + (size_t)(t + 2) * kstep;
;             const char* a3 = a2 + kstep; const char* b3 = b2 + kstep;
;             if (last && has_next) S.a_ready(nxt);
;             if constexpr (SP2) {
;             PG8_LDB(B0, 0, 0); PG8_LDB(B1, 0, 1); PG8_SCHED; PG8_LDA(At, 0, 0); PG8_STAGE(PG8_SA(1, 1), a1 + hstep, voffA);
;             PG8_WAIT_V(8); PG8_WAIT_L(0); PG8_BAR; PG8_MMA(0, 0, At, B0); PG8_MMA(0, 1, At, B1); PG8_BAR; PG8_SCHED;
;             PG8_LDA(At, 0, 1); PG8_STAGE(PG8_SB(0, 0), b2, voffB); PG8_STAGE(PG8_SB(0, 1), b2 + hstep, voffB); PG8_STAGE(PG8_SA(0, 0), a2, voffA);
.LBB0_509:
	s_add_u32 s2, s0, 0xfffc0080
	s_addc_u32 s3, s1, -1
	s_add_i32 s41, 0, 0x10000
	s_cmp_eq_u32 s40, 12
	s_cselect_b32 s9, s4, s3
	s_cselect_b32 s8, s5, s2
	v_add_u32_e32 v155, s41, v147
	s_cselect_b32 s3, s11, s39
	s_cselect_b32 s2, s24, s25
	s_add_i32 s46, 0, 0x14000
	ds_read_b128 v[128:131], v155
	ds_read_b128 v[132:135], v155 offset:1024
	ds_read_b128 v[156:159], v155 offset:2048
	ds_read_b128 v[170:173], v155 offset:3072
	v_add_u32_e32 v155, s46, v147
	ds_read_b128 v[174:177], v155
	ds_read_b128 v[178:181], v155 offset:1024
	ds_read_b128 v[194:197], v155 offset:2048
	ds_read_b128 v[198:201], v155 offset:3072
	v_lshl_add_u64 v[160:161], s[0:1], 0, v[150:151]
	s_add_i32 m0, s27, 0xc000
	ds_read_b128 v[202:205], v168
	ds_read_b128 v[206:209], v168 offset:1024
	ds_read_b128 v[210:213], v168 offset:2048
	ds_read_b128 v[228:231], v168 offset:3072
	ds_read_b128 v[232:235], v168 offset:4096
	ds_read_b128 v[236:239], v168 offset:5120
	ds_read_b128 v[240:243], v168 offset:6144
	ds_read_b128 v[244:247], v168 offset:7168
	global_load_lds_dwordx4 v[160:161], off
	v_lshl_add_u64 v[160:161], s[0:1], 0, v[152:153]
	s_add_i32 m0, s27, 0xe000
	s_nop 0
	global_load_lds_dwordx4 v[160:161], off
	s_nop 0
	s_nop 0
	s_waitcnt vmcnt(8)
	s_waitcnt lgkmcnt(0)
	s_barrier
	s_setprio 1
	s_waitcnt lgkmcnt(0)
	v_mfma_f32_16x16x32_bf16 v[124:127], v[128:131], v[202:205], v[124:127]
	v_mfma_f32_16x16x32_bf16 v[120:123], v[156:159], v[202:205], v[120:123]
	v_mfma_f32_16x16x32_bf16 v[108:111], v[128:131], v[210:213], v[108:111]
	v_mfma_f32_16x16x32_bf16 v[104:107], v[156:159], v[210:213], v[104:107]
	v_mfma_f32_16x16x32_bf16 v[92:95], v[128:131], v[232:235], v[92:95]
	v_mfma_f32_16x16x32_bf16 v[88:91], v[156:159], v[232:235], v[88:91]
	v_mfma_f32_16x16x32_bf16 v[76:79], v[128:131], v[240:243], v[76:79]
	v_mfma_f32_16x16x32_bf16 v[72:75], v[156:159], v[240:243], v[72:75]
	v_mfma_f32_16x16x32_bf16 v[124:127], v[132:135], v[206:209], v[124:127]
	v_mfma_f32_16x16x32_bf16 v[120:123], v[170:173], v[206:209], v[120:123]
	v_mfma_f32_16x16x32_bf16 v[108:111], v[132:135], v[228:231], v[108:111]
	v_mfma_f32_16x16x32_bf16 v[104:107], v[170:173], v[228:231], v[104:107]
	v_mfma_f32_16x16x32_bf16 v[92:95], v[132:135], v[236:239], v[92:95]
	v_mfma_f32_16x16x32_bf16 v[88:91], v[170:173], v[236:239], v[88:91]
	v_mfma_f32_16x16x32_bf16 v[76:79], v[132:135], v[244:247], v[76:79]
	v_mfma_f32_16x16x32_bf16 v[72:75], v[170:173], v[244:247], v[72:75]
	s_setprio 0
	s_setprio 1
	v_mfma_f32_16x16x32_bf16 v[116:119], v[174:177], v[202:205], v[116:119]
	v_mfma_f32_16x16x32_bf16 v[112:115], v[194:197], v[202:205], v[112:115]
	v_mfma_f32_16x16x32_bf16 v[100:103], v[174:177], v[210:213], v[100:103]
	v_mfma_f32_16x16x32_bf16 v[96:99], v[194:197], v[210:213], v[96:99]
	v_mfma_f32_16x16x32_bf16 v[84:87], v[174:177], v[232:235], v[84:87]
	v_mfma_f32_16x16x32_bf16 v[80:83], v[194:197], v[232:235], v[80:83]
	v_mfma_f32_16x16x32_bf16 v[68:71], v[174:177], v[240:243], v[68:71]
	v_mfma_f32_16x16x32_bf16 v[64:67], v[194:197], v[240:243], v[64:67]
	v_mfma_f32_16x16x32_bf16 v[116:119], v[178:181], v[206:209], v[116:119]
	v_mfma_f32_16x16x32_bf16 v[112:115], v[198:201], v[206:209], v[112:115]
	v_mfma_f32_16x16x32_bf16 v[100:103], v[178:181], v[228:231], v[100:103]
	v_mfma_f32_16x16x32_bf16 v[96:99], v[198:201], v[228:231], v[96:99]
	v_mfma_f32_16x16x32_bf16 v[84:87], v[178:181], v[236:239], v[84:87]
	v_mfma_f32_16x16x32_bf16 v[80:83], v[198:201], v[236:239], v[80:83]
	v_mfma_f32_16x16x32_bf16 v[68:71], v[178:181], v[244:247], v[68:71]
	v_mfma_f32_16x16x32_bf16 v[64:67], v[198:201], v[244:247], v[64:67]
	s_setprio 0
	s_barrier
	s_add_i32 s41, s41, s26
	v_lshl_add_u64 v[160:161], s[2:3], 0, v[140:141]
	s_mov_b32 m0, s41
	ds_read_b128 v[202:205], v168 offset:16384
	ds_read_b128 v[206:209], v168 offset:17408
	ds_read_b128 v[210:213], v168 offset:18432
	ds_read_b128 v[228:231], v168 offset:19456
	ds_read_b128 v[232:235], v168 offset:20480
	ds_read_b128 v[236:239], v168 offset:21504
	ds_read_b128 v[240:243], v168 offset:22528
	ds_read_b128 v[244:247], v168 offset:23552
	global_load_lds_dwordx4 v[160:161], off
	s_add_i32 m0, s41, 0x2000
	s_add_u32 s44, s2, 0x40000
	v_lshl_add_u64 v[182:183], s[2:3], 0, v[136:137]
	s_addc_u32 s45, s3, 0
	s_add_i32 s41, s46, s26
	global_load_lds_dwordx4 v[182:183], off
	v_lshl_add_u64 v[214:215], s[44:45], 0, v[140:141]
	s_mov_b32 m0, s41
	v_lshl_add_u64 v[248:249], s[8:9], 0, v[138:139]
	global_load_lds_dwordx4 v[214:215], off
	v_lshl_add_u64 v[214:215], s[44:45], 0, v[136:137]
	s_add_i32 m0, s41, 0x2000
	s_nop 0
	global_load_lds_dwordx4 v[214:215], off
	v_lshl_add_u64 v[214:215], s[8:9], 0, v[142:143]
	s_mov_b32 m0, s27
	s_nop 0
	global_load_lds_dwordx4 v[214:215], off
	s_mov_b32 m0, s28
	s_nop 0
	global_load_lds_dwordx4 v[248:249], off
	s_nop 0
	s_waitcnt vmcnt(8)
	s_waitcnt lgkmcnt(0)
	s_barrier
; #define PG8_STAGE(bufoff, gbase, voff) do { _Pragma("unroll") for (int _i = 0; _i < 2; ++_i) \
;         __builtin_amdgcn_global_load_lds((const unsigned*)((const char*)(gbase) + (voff)[_i]), (PG8_LAS unsigned*)(lds + (bufoff) + ldsw + _i * 8192), 16, 0, 0); } while (0)
; #define PG8_LDA(dst, b, h) do { _Pragma("unroll") for (int m = 0; m < 4; ++m) _Pragma("unroll") for (int k = 0; k < 2; ++k) dst[m][k] = *(const PG8_LAS bf16x8*)(lds + PG8_SA(b, h) + aoff + m * 2048 + k * 1024); } while (0)
; #define PG8_LDB(dst, b, h) do { _Pragma("unroll") for (int n = 0; n < 2; ++n) _Pragma("unroll") for (int k = 0; k < 2; ++k) dst[n][k] = *(const PG8_LAS bf16x8*)(lds + PG8_SB(b, h) + boff + n * 2048 + k * 1024); } while (0)
; #define PG8_MMA(ai, bj, At, Bt) do { __builtin_amdgcn_s_setprio(1); _Pragma("unroll") for (int m = 0; m < 4; ++m) _Pragma("unroll") for (int n = 0; n < 2; ++n) _Pragma("unroll") for (int k = 0; k < 2; ++k) \
;         acc[ai][bj][m][n] = __builtin_amdgcn_mfma_f32_16x16x32_bf16(Bt[n][k], At[m][k], acc[ai][bj][m][n], 0, 0, 0); __builtin_amdgcn_s_setprio(0); } while (0)
; #define PG8_WAIT_V(n) asm volatile("s_waitcnt vmcnt(" #n ")" ::: "memory")
; #define PG8_WAIT_L(n) asm volatile("s_waitcnt lgkmcnt(" #n ")" ::: "memory")
; #define PG8_BAR __builtin_amdgcn_s_barrier()
; #define PG8_SCHED __builtin_amdgcn_sched_barrier(0)
; template <class Epi, class Sched, bool ALIGN_EPI = false, bool SP2 = false>
; __device__ __forceinline__ void gemm_phase(PG8_LAS unsigned char* lds, const Gemm g, const Sched& S, const Epi& E) {
;     ...
;             PG8_WAIT_V(8); PG8_WAIT_L(0); PG8_BAR; PG8_MMA(1, 0, At, B0); PG8_MMA(1, 1, At, B1); PG8_BAR; PG8_SCHED;
;             PG8_LDB(B0, 1, 0); PG8_LDB(B1, 1, 1); PG8_SCHED; PG8_LDA(At, 1, 0); PG8_STAGE(PG8_SA(0, 1), a2 + hstep, voffA);
;             PG8_WAIT_V(8); PG8_WAIT_L(0); PG8_BAR; PG8_MMA(0, 0, At, B0); PG8_MMA(0, 1, At, B1); PG8_BAR; PG8_SCHED;
	s_setprio 1
	s_waitcnt lgkmcnt(0)
	v_mfma_f32_16x16x32_bf16 v[60:63], v[128:131], v[202:205], v[60:63]
	v_mfma_f32_16x16x32_bf16 v[56:59], v[156:159], v[202:205], v[56:59]
	v_mfma_f32_16x16x32_bf16 v[44:47], v[128:131], v[210:213], v[44:47]
	v_mfma_f32_16x16x32_bf16 v[40:43], v[156:159], v[210:213], v[40:43]
	v_mfma_f32_16x16x32_bf16 v[28:31], v[128:131], v[232:235], v[28:31]
	v_mfma_f32_16x16x32_bf16 v[24:27], v[156:159], v[232:235], v[24:27]
	v_mfma_f32_16x16x32_bf16 v[12:15], v[128:131], v[240:243], v[12:15]
	v_mfma_f32_16x16x32_bf16 v[8:11], v[156:159], v[240:243], v[8:11]
	v_mfma_f32_16x16x32_bf16 v[60:63], v[132:135], v[206:209], v[60:63]
	v_mfma_f32_16x16x32_bf16 v[56:59], v[170:173], v[206:209], v[56:59]
	v_mfma_f32_16x16x32_bf16 v[44:47], v[132:135], v[228:231], v[44:47]
	v_mfma_f32_16x16x32_bf16 v[40:43], v[170:173], v[228:231], v[40:43]
	v_mfma_f32_16x16x32_bf16 v[28:31], v[132:135], v[236:239], v[28:31]
	v_mfma_f32_16x16x32_bf16 v[24:27], v[170:173], v[236:239], v[24:27]
	v_mfma_f32_16x16x32_bf16 v[12:15], v[132:135], v[244:247], v[12:15]
	v_mfma_f32_16x16x32_bf16 v[8:11], v[170:173], v[244:247], v[8:11]
	s_setprio 0
	s_setprio 1
	v_mfma_f32_16x16x32_bf16 v[52:55], v[174:177], v[202:205], v[52:55]
	v_mfma_f32_16x16x32_bf16 v[48:51], v[194:197], v[202:205], v[48:51]
	v_mfma_f32_16x16x32_bf16 v[36:39], v[174:177], v[210:213], v[36:39]
	v_mfma_f32_16x16x32_bf16 v[32:35], v[194:197], v[210:213], v[32:35]
	v_mfma_f32_16x16x32_bf16 v[20:23], v[174:177], v[232:235], v[20:23]
	v_mfma_f32_16x16x32_bf16 v[16:19], v[194:197], v[232:235], v[16:19]
	v_mfma_f32_16x16x32_bf16 v[4:7], v[174:177], v[240:243], v[4:7]
	v_mfma_f32_16x16x32_bf16 v[0:3], v[194:197], v[240:243], v[0:3]
	v_mfma_f32_16x16x32_bf16 v[52:55], v[178:181], v[206:209], v[52:55]
	v_mfma_f32_16x16x32_bf16 v[48:51], v[198:201], v[206:209], v[48:51]
	v_mfma_f32_16x16x32_bf16 v[36:39], v[178:181], v[228:231], v[36:39]
	v_mfma_f32_16x16x32_bf16 v[32:35], v[198:201], v[228:231], v[32:35]
	v_mfma_f32_16x16x32_bf16 v[20:23], v[178:181], v[236:239], v[20:23]
	v_mfma_f32_16x16x32_bf16 v[16:19], v[198:201], v[236:239], v[16:19]
	v_mfma_f32_16x16x32_bf16 v[4:7], v[178:181], v[244:247], v[4:7]
	v_mfma_f32_16x16x32_bf16 v[0:3], v[198:201], v[244:247], v[0:3]
	s_setprio 0
	s_barrier
	s_add_i32 s41, 0, 0x18000
	v_add_u32_e32 v155, s41, v147
	s_add_i32 s44, 0, 0x1c000
	ds_read_b128 v[128:131], v155
	ds_read_b128 v[132:135], v155 offset:1024
	ds_read_b128 v[156:159], v155 offset:2048
	ds_read_b128 v[170:173], v155 offset:3072
	v_add_u32_e32 v155, s44, v147
	ds_read_b128 v[174:177], v155
	ds_read_b128 v[178:181], v155 offset:1024
	ds_read_b128 v[194:197], v155 offset:2048
	ds_read_b128 v[198:201], v155 offset:3072
	s_add_u32 s8, s8, 0x40000
	s_addc_u32 s9, s9, 0
	s_mov_b32 m0, s29
	v_lshl_add_u64 v[224:225], s[8:9], 0, v[142:143]
	ds_read_b128 v[202:205], v168 offset:32768
	ds_read_b128 v[206:209], v168 offset:33792
	ds_read_b128 v[210:213], v168 offset:34816
	ds_read_b128 v[228:231], v168 offset:35840
	ds_read_b128 v[232:235], v168 offset:36864
	ds_read_b128 v[236:239], v168 offset:37888
	ds_read_b128 v[240:243], v168 offset:38912
	ds_read_b128 v[244:247], v168 offset:39936
	global_load_lds_dwordx4 v[224:225], off
	v_lshl_add_u64 v[224:225], s[8:9], 0, v[138:139]
	s_mov_b32 m0, s30
	s_nop 0
	global_load_lds_dwordx4 v[224:225], off
	s_nop 0
	s_waitcnt vmcnt(8)
	s_waitcnt lgkmcnt(0)
	s_barrier
	s_setprio 1
	s_waitcnt lgkmcnt(0)
	v_mfma_f32_16x16x32_bf16 v[124:127], v[128:131], v[202:205], v[124:127]
	v_mfma_f32_16x16x32_bf16 v[120:123], v[156:159], v[202:205], v[120:123]
	v_mfma_f32_16x16x32_bf16 v[108:111], v[128:131], v[210:213], v[108:111]
	v_mfma_f32_16x16x32_bf16 v[104:107], v[156:159], v[210:213], v[104:107]
	v_mfma_f32_16x16x32_bf16 v[92:95], v[128:131], v[232:235], v[92:95]
	v_mfma_f32_16x16x32_bf16 v[88:91], v[156:159], v[232:235], v[88:91]
	v_mfma_f32_16x16x32_bf16 v[76:79], v[128:131], v[240:243], v[76:79]
	v_mfma_f32_16x16x32_bf16 v[72:75], v[156:159], v[240:243], v[72:75]
	v_mfma_f32_16x16x32_bf16 v[124:127], v[132:135], v[206:209], v[124:127]
	v_mfma_f32_16x16x32_bf16 v[120:123], v[170:173], v[206:209], v[120:123]
	v_mfma_f32_16x16x32_bf16 v[108:111], v[132:135], v[228:231], v[108:111]
	v_mfma_f32_16x16x32_bf16 v[104:107], v[170:173], v[228:231], v[104:107]
	v_mfma_f32_16x16x32_bf16 v[92:95], v[132:135], v[236:239], v[92:95]
	v_mfma_f32_16x16x32_bf16 v[88:91], v[170:173], v[236:239], v[88:91]
	v_mfma_f32_16x16x32_bf16 v[76:79], v[132:135], v[244:247], v[76:79]
	v_mfma_f32_16x16x32_bf16 v[72:75], v[170:173], v[244:247], v[72:75]
	s_setprio 0
	s_setprio 1
	v_mfma_f32_16x16x32_bf16 v[116:119], v[174:177], v[202:205], v[116:119]
	v_mfma_f32_16x16x32_bf16 v[112:115], v[194:197], v[202:205], v[112:115]
	v_mfma_f32_16x16x32_bf16 v[100:103], v[174:177], v[210:213], v[100:103]
	v_mfma_f32_16x16x32_bf16 v[96:99], v[194:197], v[210:213], v[96:99]
	v_mfma_f32_16x16x32_bf16 v[84:87], v[174:177], v[232:235], v[84:87]
	v_mfma_f32_16x16x32_bf16 v[80:83], v[194:197], v[232:235], v[80:83]
	v_mfma_f32_16x16x32_bf16 v[68:71], v[174:177], v[240:243], v[68:71]
	v_mfma_f32_16x16x32_bf16 v[64:67], v[194:197], v[240:243], v[64:67]
	v_mfma_f32_16x16x32_bf16 v[116:119], v[178:181], v[206:209], v[116:119]
	v_mfma_f32_16x16x32_bf16 v[112:115], v[198:201], v[206:209], v[112:115]
	v_mfma_f32_16x16x32_bf16 v[100:103], v[178:181], v[228:231], v[100:103]
	v_mfma_f32_16x16x32_bf16 v[96:99], v[198:201], v[228:231], v[96:99]
	v_mfma_f32_16x16x32_bf16 v[84:87], v[178:181], v[236:239], v[84:87]
	v_mfma_f32_16x16x32_bf16 v[80:83], v[198:201], v[236:239], v[80:83]
	v_mfma_f32_16x16x32_bf16 v[68:71], v[178:181], v[244:247], v[68:71]
	v_mfma_f32_16x16x32_bf16 v[64:67], v[198:201], v[244:247], v[64:67]
	s_setprio 0
	s_barrier
; #define PG8_STAGE(bufoff, gbase, voff) do { _Pragma("unroll") for (int _i = 0; _i < 2; ++_i) \
;         __builtin_amdgcn_global_load_lds((const unsigned*)((const char*)(gbase) + (voff)[_i]), (PG8_LAS unsigned*)(lds + (bufoff) + ldsw + _i * 8192), 16, 0, 0); } while (0)
; #define PG8_LDA(dst, b, h) do { _Pragma("unroll") for (int m = 0; m < 4; ++m) _Pragma("unroll") for (int k = 0; k < 2; ++k) dst[m][k] = *(const PG8_LAS bf16x8*)(lds + PG8_SA(b, h) + aoff + m * 2048 + k * 1024); } while (0)
; #define PG8_MMA(ai, bj, At, Bt) do { __builtin_amdgcn_s_setprio(1); _Pragma("unroll") for (int m = 0; m < 4; ++m) _Pragma("unroll") for (int n = 0; n < 2; ++n) _Pragma("unroll") for (int k = 0; k < 2; ++k) \
;         acc[ai][bj][m][n] = __builtin_amdgcn_mfma_f32_16x16x32_bf16(Bt[n][k], At[m][k], acc[ai][bj][m][n], 0, 0, 0); __builtin_amdgcn_s_setprio(0); } while (0)
; #define PG8_WAIT_V(n) asm volatile("s_waitcnt vmcnt(" #n ")" ::: "memory")
; #define PG8_WAIT_L(n) asm volatile("s_waitcnt lgkmcnt(" #n ")" ::: "memory")
; #define PG8_BAR __builtin_amdgcn_s_barrier()
;     __device__ __forceinline__ void operator()(const f32x4 (&acc)[2][2][4][2], const Unit& u, int wr, int wc, int fr, int fq) const {
;     ...
;             bf16_t* MVT = (bf16_t*)(ws + WS_MVT); float* o_mv = out + O_MVP;
; #pragma unroll
;             for (int ai = 0; ai < 2; ++ai)
; #pragma unroll
;                 for (int m = 0; m < 4; ++m) {
;                     int mrow = ai * HALF + wr * 64 + m * 16 + fr;
;                     asm volatile("" : "+v"(mrow));
;                     const float rs = MRS[b * 256 + mrow];
; #pragma unroll
;                     for (int bj = 0; bj < 2; ++bj) {
;                         const f32x4 v0 = acc[ai][bj][m][0] * rs, v1 = acc[ai][bj][m][1] * rs;
;                         const int c0 = wc * 64 + bj * 32 + 8 * fq;
;                         bf16_t* vp = MVT + ((size_t)(l * 40 + b) * 256 + c0) * 256 + mrow;
; template <class Epi, class Sched, bool ALIGN_EPI = false, bool SP2 = false>
; __device__ __forceinline__ void gemm_phase(PG8_LAS unsigned char* lds, const Gemm g, const Sched& S, const Epi& E) {
;     ...
;             PG8_LDA(At, 1, 1); PG8_STAGE(PG8_SB(1, 0), b3, voffB); PG8_STAGE(PG8_SB(1, 1), b3 + hstep, voffB); PG8_STAGE(PG8_SA(1, 0), a3, voffA);
;             PG8_WAIT_V(8); PG8_WAIT_L(0); PG8_BAR; PG8_MMA(1, 0, At, B0); PG8_MMA(1, 1, At, B1); PG8_BAR; PG8_SCHED;
	s_add_i32 s8, s41, s26
	v_lshl_add_u64 v[160:161], v[160:161], 0, s[96:97]
	s_mov_b32 m0, s8
	ds_read_b128 v[202:205], v168 offset:49152
	ds_read_b128 v[206:209], v168 offset:50176
	ds_read_b128 v[210:213], v168 offset:51200
	ds_read_b128 v[228:231], v168 offset:52224
	ds_read_b128 v[232:235], v168 offset:53248
	ds_read_b128 v[236:239], v168 offset:54272
	ds_read_b128 v[240:243], v168 offset:55296
	ds_read_b128 v[244:247], v168 offset:56320
	global_load_lds_dwordx4 v[160:161], off
	s_add_i32 m0, s8, 0x2000
	s_add_u32 s2, s2, 0x40080
	v_lshl_add_u64 v[160:161], v[182:183], 0, s[96:97]
	s_addc_u32 s3, s3, 0
	s_add_i32 s8, s44, s26
	global_load_lds_dwordx4 v[160:161], off
	v_lshl_add_u64 v[160:161], s[2:3], 0, v[140:141]
	s_mov_b32 m0, s8
	s_nop 0
	global_load_lds_dwordx4 v[160:161], off
	v_lshl_add_u64 v[160:161], s[2:3], 0, v[136:137]
	s_add_i32 m0, s8, 0x2000
	s_nop 0
	global_load_lds_dwordx4 v[160:161], off
	v_lshl_add_u64 v[160:161], v[214:215], 0, s[96:97]
	s_mov_b32 m0, s31
	s_nop 0
	global_load_lds_dwordx4 v[160:161], off
	v_lshl_add_u64 v[160:161], v[248:249], 0, s[96:97]
	s_mov_b32 m0, s34
	s_nop 0
	global_load_lds_dwordx4 v[160:161], off
	s_waitcnt vmcnt(8)
	s_waitcnt lgkmcnt(0)
	s_barrier
	s_setprio 1
	s_waitcnt lgkmcnt(0)
	v_mfma_f32_16x16x32_bf16 v[60:63], v[128:131], v[202:205], v[60:63]
	v_mfma_f32_16x16x32_bf16 v[56:59], v[156:159], v[202:205], v[56:59]
	v_mfma_f32_16x16x32_bf16 v[44:47], v[128:131], v[210:213], v[44:47]
	v_mfma_f32_16x16x32_bf16 v[40:43], v[156:159], v[210:213], v[40:43]
	v_mfma_f32_16x16x32_bf16 v[28:31], v[128:131], v[232:235], v[28:31]
	v_mfma_f32_16x16x32_bf16 v[24:27], v[156:159], v[232:235], v[24:27]
	v_mfma_f32_16x16x32_bf16 v[12:15], v[128:131], v[240:243], v[12:15]
	v_mfma_f32_16x16x32_bf16 v[8:11], v[156:159], v[240:243], v[8:11]
	v_mfma_f32_16x16x32_bf16 v[60:63], v[132:135], v[206:209], v[60:63]
	v_mfma_f32_16x16x32_bf16 v[56:59], v[170:173], v[206:209], v[56:59]
	v_mfma_f32_16x16x32_bf16 v[44:47], v[132:135], v[228:231], v[44:47]
	v_mfma_f32_16x16x32_bf16 v[40:43], v[170:173], v[228:231], v[40:43]
	v_mfma_f32_16x16x32_bf16 v[28:31], v[132:135], v[236:239], v[28:31]
	v_mfma_f32_16x16x32_bf16 v[24:27], v[170:173], v[236:239], v[24:27]
	v_mfma_f32_16x16x32_bf16 v[12:15], v[132:135], v[244:247], v[12:15]
	v_mfma_f32_16x16x32_bf16 v[8:11], v[170:173], v[244:247], v[8:11]
	s_setprio 0
	s_setprio 1
	v_mfma_f32_16x16x32_bf16 v[52:55], v[174:177], v[202:205], v[52:55]
	v_mfma_f32_16x16x32_bf16 v[48:51], v[194:197], v[202:205], v[48:51]
	v_mfma_f32_16x16x32_bf16 v[36:39], v[174:177], v[210:213], v[36:39]
	v_mfma_f32_16x16x32_bf16 v[32:35], v[194:197], v[210:213], v[32:35]
	v_mfma_f32_16x16x32_bf16 v[20:23], v[174:177], v[232:235], v[20:23]
	v_mfma_f32_16x16x32_bf16 v[16:19], v[194:197], v[232:235], v[16:19]
	v_mfma_f32_16x16x32_bf16 v[4:7], v[174:177], v[240:243], v[4:7]
	v_mfma_f32_16x16x32_bf16 v[0:3], v[194:197], v[240:243], v[0:3]
	v_mfma_f32_16x16x32_bf16 v[52:55], v[178:181], v[206:209], v[52:55]
	v_mfma_f32_16x16x32_bf16 v[48:51], v[198:201], v[206:209], v[48:51]
	v_mfma_f32_16x16x32_bf16 v[36:39], v[178:181], v[228:231], v[36:39]
	v_mfma_f32_16x16x32_bf16 v[32:35], v[198:201], v[228:231], v[32:35]
	v_mfma_f32_16x16x32_bf16 v[20:23], v[178:181], v[236:239], v[20:23]
	v_mfma_f32_16x16x32_bf16 v[16:19], v[198:201], v[236:239], v[16:19]
	v_mfma_f32_16x16x32_bf16 v[4:7], v[178:181], v[244:247], v[4:7]
	v_mfma_f32_16x16x32_bf16 v[0:3], v[198:201], v[244:247], v[0:3]
	s_setprio 0
	s_barrier
	s_add_i32 s40, s40, 2
	s_add_u32 s0, s0, 0x100
	s_addc_u32 s1, s1, 0
	s_add_u32 s25, s25, 0x100
	s_addc_u32 s39, s39, 0
	s_cmp_gt_u32 s40, 13
	s_cbranch_scc0 .LBB0_509
	s_and_b64 vcc, exec, s[16:17]
	s_cbranch_vccz .LBB0_512
	s_barrier
.LBB0_512:
	s_ashr_i32 s4, s15, 1
	s_bitcmp1_b32 s15, 0
	s_cselect_b64 s[2:3], -1, 0
	s_mov_b64 s[0:1], -1
	s_and_b64 vcc, exec, s[2:3]
	s_mul_i32 s5, s4, 40
	s_cbranch_vccz .LBB0_515
	s_lshl_b32 s8, s14, 8
	v_mov_b32_e32 v128, v145
	s_add_i32 s0, s5, s14
	v_add_u32_e32 v130, s8, v128
	v_ashrrev_i32_e32 v131, 31, v130
	v_lshl_add_u64 v[130:131], v[130:131], 2, s[20:21]
	global_load_dword v134, v[130:131], off
	v_add_u32_e32 v130, s8, v149
	v_ashrrev_i32_e32 v131, 31, v130
	v_lshl_add_u64 v[130:131], v[130:131], 2, s[20:21]
	global_load_dword v190, v[130:131], off
	v_add_u32_e32 v130, s8, v162
	v_ashrrev_i32_e32 v131, 31, v130
	v_lshl_add_u64 v[130:131], v[130:131], 2, s[20:21]
	global_load_dword v191, v[130:131], off
	v_add_u32_e32 v130, s8, v163
	v_ashrrev_i32_e32 v131, 31, v130
	v_lshl_add_u64 v[130:131], v[130:131], 2, s[20:21]
	global_load_dword v217, v[130:131], off
	v_add_u32_e32 v130, s8, v164
	v_ashrrev_i32_e32 v131, 31, v130
	v_lshl_add_u64 v[130:131], v[130:131], 2, s[20:21]
	global_load_dword v220, v[130:131], off
	v_add_u32_e32 v130, s8, v165
	v_ashrrev_i32_e32 v131, 31, v130
	v_lshl_add_u64 v[130:131], v[130:131], 2, s[20:21]
	global_load_dword v223, v[130:131], off
	v_add_u32_e32 v130, s8, v166
	v_ashrrev_i32_e32 v131, 31, v130
	v_lshl_add_u64 v[130:131], v[130:131], 2, s[20:21]
	global_load_dword v226, v[130:131], off
	v_add_u32_e32 v130, s8, v167
	v_ashrrev_i32_e32 v131, 31, v130
	v_lshl_add_u64 v[130:131], v[130:131], 2, s[20:21]
	global_load_dword v250, v[130:131], off
	s_ashr_i32 s1, s0, 31
	s_lshl_b64 s[2:3], s[0:1], 16
	s_lshl_b32 s1, s4, 5
	s_sub_i32 s0, s0, s1
	s_ashr_i32 s1, s0, 31
	s_lshl_b64 s[0:1], s[0:1], 18
	v_readlane_b32 s9, v251, 43
	s_add_u32 s0, s9, s0
	v_readlane_b32 s9, v251, 44
	v_ashrrev_i32_e32 v129, 31, v128
	s_addc_u32 s1, s9, s1
	v_lshl_add_u64 v[170:171], v[128:129], 1, s[22:23]
	v_lshlrev_b64 v[128:129], 10, v[128:129]
	v_lshl_add_u64 v[160:161], s[0:1], 0, v[128:129]
	v_mov_b32_e32 v129, s3
	v_or_b32_e32 v128, s2, v146
	v_lshlrev_b64 v[128:129], 1, v[128:129]
	v_lshl_add_u64 v[172:173], v[170:171], 0, v[128:129]
	v_mov_b32_e32 v155, v185
	s_waitcnt vmcnt(0)
; __device__ __forceinline__ bf16_t f2bf1(float f) { return (bf16_t)(cvt_pk_bf16(f, 0.f) & 0xffffu); }
;     __device__ __forceinline__ void operator()(const f32x4 (&acc)[2][2][4][2], const Unit& u, int wr, int wc, int fr, int fq) const {
;     ...
;             for (int ai = 0; ai < 2; ++ai)
; #pragma unroll
;                 for (int m = 0; m < 4; ++m) {
;                     int mrow = ai * HALF + wr * 64 + m * 16 + fr;
;                     asm volatile("" : "+v"(mrow));
;                     const float rs = MRS[b * 256 + mrow];
; #pragma unroll
;                     for (int bj = 0; bj < 2; ++bj) {
;                         const f32x4 v0 = acc[ai][bj][m][0] * rs, v1 = acc[ai][bj][m][1] * rs;
;                         const int c0 = wc * 64 + bj * 32 + 8 * fq;
;                         bf16_t* vp = MVT + ((size_t)(l * 40 + b) * 256 + c0) * 256 + mrow;
; #pragma unroll
;                         for (int j = 0; j < 4; ++j) { vp[j * 256] = f2bf1(v0[j]); vp[(4 + j) * 256] = f2bf1(v1[j]); }
;                         float* d = o_mv + ((size_t)(l * 8 + b) * 256 + mrow) * 256 + c0; __builtin_nontemporal_store(v0, (f32x4*)d); __builtin_nontemporal_store(v1, (f32x4*)(d + 4));
;                     }
	v_pk_mul_f32 v[132:133], v[126:127], v[134:135] op_sel_hi:[1,0]
	v_pk_mul_f32 v[130:131], v[124:125], v[134:135] op_sel_hi:[1,0]
	v_pk_mul_f32 v[158:159], v[122:123], v[134:135] op_sel_hi:[1,0]
	v_pk_mul_f32 v[156:157], v[120:121], v[134:135] op_sel_hi:[1,0]
	v_cvt_pk_bf16_f32 v135, v130, v185
	global_store_short v[172:173], v135, off
	v_cvt_pk_bf16_f32 v135, v156, v185
	global_store_short v[172:173], v135, off offset:2048
	v_cvt_pk_bf16_f32 v135, v131, v185
	global_store_short v[172:173], v135, off offset:512
	v_cvt_pk_bf16_f32 v135, v157, v185
	global_store_short v[172:173], v135, off offset:2560
	v_cvt_pk_bf16_f32 v135, v132, v185
	global_store_short v[172:173], v135, off offset:1024
	v_cvt_pk_bf16_f32 v135, v158, v185
	global_store_short v[172:173], v135, off offset:3072
	v_cvt_pk_bf16_f32 v135, v133, v185
	global_store_short v[172:173], v135, off offset:1536
	v_cvt_pk_bf16_f32 v135, v159, v185
	global_store_short v[172:173], v135, off offset:3584
	v_lshl_add_u64 v[172:173], v[160:161], 0, v[154:155]
	global_store_dwordx4 v[172:173], v[130:133], off nt
	global_store_dwordx4 v[172:173], v[156:159], off offset:16 nt
	v_pk_mul_f32 v[160:161], v[114:115], v[134:135] op_sel_hi:[1,0]
	v_pk_mul_f32 v[132:133], v[118:119], v[134:135] op_sel_hi:[1,0]
	v_pk_mul_f32 v[130:131], v[116:117], v[134:135] op_sel_hi:[1,0]
	v_pk_mul_f32 v[158:159], v[112:113], v[134:135] op_sel_hi:[1,0]
	v_mov_b32_e32 v135, s3
	v_or_b32_e32 v134, s2, v148
	v_lshlrev_b64 v[156:157], 1, v[134:135]
	v_lshl_add_u64 v[134:135], v[170:171], 0, v[156:157]
	v_cvt_pk_bf16_f32 v170, v130, v185
	global_store_short v[134:135], v170, off
	v_cvt_pk_bf16_f32 v170, v158, v185
	global_store_short v[134:135], v170, off offset:2048
	v_cvt_pk_bf16_f32 v170, v131, v185
	global_store_short v[134:135], v170, off offset:512
	v_cvt_pk_bf16_f32 v170, v159, v185
	global_store_short v[134:135], v170, off offset:2560
	v_cvt_pk_bf16_f32 v170, v132, v185
	global_store_short v[134:135], v170, off offset:1024
	v_cvt_pk_bf16_f32 v170, v160, v185
	global_store_short v[134:135], v170, off offset:3072
	v_cvt_pk_bf16_f32 v170, v133, v185
	global_store_short v[134:135], v170, off offset:1536
	v_cvt_pk_bf16_f32 v170, v161, v185
	global_store_short v[134:135], v170, off offset:3584
	global_store_dwordx4 v[172:173], v[130:133], off offset:128 nt
	global_store_dwordx4 v[172:173], v[158:161], off offset:144 nt
	s_nop 0
	v_mov_b32_e32 v130, v149
	s_nop 0
	v_mov_b32_e32 v134, v190
	v_ashrrev_i32_e32 v131, 31, v130
	v_lshl_add_u64 v[170:171], v[130:131], 1, s[22:23]
	v_lshlrev_b64 v[130:131], 10, v[130:131]
	v_lshl_add_u64 v[172:173], s[0:1], 0, v[130:131]
	v_lshl_add_u64 v[174:175], v[170:171], 0, v[128:129]
	v_lshl_add_u64 v[172:173], v[172:173], 0, v[154:155]
	v_pk_mul_f32 v[132:133], v[110:111], v[134:135] op_sel_hi:[1,0]
	v_pk_mul_f32 v[130:131], v[108:109], v[134:135] op_sel_hi:[1,0]
	v_pk_mul_f32 v[160:161], v[106:107], v[134:135] op_sel_hi:[1,0]
	v_pk_mul_f32 v[158:159], v[104:105], v[134:135] op_sel_hi:[1,0]
	v_cvt_pk_bf16_f32 v135, v130, v185
	global_store_short v[174:175], v135, off
	v_cvt_pk_bf16_f32 v135, v158, v185
	global_store_short v[174:175], v135, off offset:2048
	v_cvt_pk_bf16_f32 v135, v131, v185
	global_store_short v[174:175], v135, off offset:512
	v_cvt_pk_bf16_f32 v135, v159, v185
	global_store_short v[174:175], v135, off offset:2560
	v_cvt_pk_bf16_f32 v135, v132, v185
	global_store_short v[174:175], v135, off offset:1024
	v_cvt_pk_bf16_f32 v135, v160, v185
	global_store_short v[174:175], v135, off offset:3072
	v_cvt_pk_bf16_f32 v135, v133, v185
	global_store_short v[174:175], v135, off offset:1536
	v_cvt_pk_bf16_f32 v135, v161, v185
	global_store_short v[174:175], v135, off offset:3584
	global_store_dwordx4 v[172:173], v[130:133], off nt
	global_store_dwordx4 v[172:173], v[158:161], off offset:16 nt
	s_nop 0
	v_pk_mul_f32 v[132:133], v[102:103], v[134:135] op_sel_hi:[1,0]
	v_pk_mul_f32 v[130:131], v[100:101], v[134:135] op_sel_hi:[1,0]
	v_pk_mul_f32 v[160:161], v[98:99], v[134:135] op_sel_hi:[1,0]
	v_pk_mul_f32 v[158:159], v[96:97], v[134:135] op_sel_hi:[1,0]
	v_lshl_add_u64 v[134:135], v[170:171], 0, v[156:157]
	v_cvt_pk_bf16_f32 v170, v130, v185
	global_store_short v[134:135], v170, off
	v_cvt_pk_bf16_f32 v170, v158, v185
	global_store_short v[134:135], v170, off offset:2048
	v_cvt_pk_bf16_f32 v170, v131, v185
	global_store_short v[134:135], v170, off offset:512
	v_cvt_pk_bf16_f32 v170, v159, v185
	global_store_short v[134:135], v170, off offset:2560
	v_cvt_pk_bf16_f32 v170, v132, v185
	global_store_short v[134:135], v170, off offset:1024
	v_cvt_pk_bf16_f32 v170, v160, v185
	global_store_short v[134:135], v170, off offset:3072
	v_cvt_pk_bf16_f32 v170, v133, v185
	global_store_short v[134:135], v170, off offset:1536
	v_cvt_pk_bf16_f32 v170, v161, v185
	global_store_short v[134:135], v170, off offset:3584
	global_store_dwordx4 v[172:173], v[130:133], off offset:128 nt
	global_store_dwordx4 v[172:173], v[158:161], off offset:144 nt
	s_nop 0
	v_mov_b32_e32 v130, v162
	s_nop 0
	v_mov_b32_e32 v134, v191
	v_ashrrev_i32_e32 v131, 31, v130
	v_lshl_add_u64 v[170:171], v[130:131], 1, s[22:23]
	v_lshlrev_b64 v[130:131], 10, v[130:131]
	v_lshl_add_u64 v[172:173], s[0:1], 0, v[130:131]
	v_lshl_add_u64 v[174:175], v[170:171], 0, v[128:129]
	v_lshl_add_u64 v[172:173], v[172:173], 0, v[154:155]
	v_pk_mul_f32 v[132:133], v[94:95], v[134:135] op_sel_hi:[1,0]
	v_pk_mul_f32 v[130:131], v[92:93], v[134:135] op_sel_hi:[1,0]
	v_pk_mul_f32 v[160:161], v[90:91], v[134:135] op_sel_hi:[1,0]
	v_pk_mul_f32 v[158:159], v[88:89], v[134:135] op_sel_hi:[1,0]
	v_cvt_pk_bf16_f32 v135, v130, v185
	global_store_short v[174:175], v135, off
; __device__ __forceinline__ bf16_t f2bf1(float f) { return (bf16_t)(cvt_pk_bf16(f, 0.f) & 0xffffu); }
;     __device__ __forceinline__ void operator()(const f32x4 (&acc)[2][2][4][2], const Unit& u, int wr, int wc, int fr, int fq) const {
;     ...
;             for (int ai = 0; ai < 2; ++ai)
; #pragma unroll
;                 for (int m = 0; m < 4; ++m) {
;                     int mrow = ai * HALF + wr * 64 + m * 16 + fr;
;                     asm volatile("" : "+v"(mrow));
;                     const float rs = MRS[b * 256 + mrow];
; #pragma unroll
;                     for (int bj = 0; bj < 2; ++bj) {
;                         const f32x4 v0 = acc[ai][bj][m][0] * rs, v1 = acc[ai][bj][m][1] * rs;
;                         const int c0 = wc * 64 + bj * 32 + 8 * fq;
;                         bf16_t* vp = MVT + ((size_t)(l * 40 + b) * 256 + c0) * 256 + mrow;
; #pragma unroll
;                         for (int j = 0; j < 4; ++j) { vp[j * 256] = f2bf1(v0[j]); vp[(4 + j) * 256] = f2bf1(v1[j]); }
;                         float* d = o_mv + ((size_t)(l * 8 + b) * 256 + mrow) * 256 + c0; __builtin_nontemporal_store(v0, (f32x4*)d); __builtin_nontemporal_store(v1, (f32x4*)(d + 4));
;                     }
	v_cvt_pk_bf16_f32 v135, v158, v185
	global_store_short v[174:175], v135, off offset:2048
	v_cvt_pk_bf16_f32 v135, v131, v185
	global_store_short v[174:175], v135, off offset:512
	v_cvt_pk_bf16_f32 v135, v159, v185
	global_store_short v[174:175], v135, off offset:2560
	v_cvt_pk_bf16_f32 v135, v132, v185
	global_store_short v[174:175], v135, off offset:1024
	v_cvt_pk_bf16_f32 v135, v160, v185
	global_store_short v[174:175], v135, off offset:3072
	v_cvt_pk_bf16_f32 v135, v133, v185
	global_store_short v[174:175], v135, off offset:1536
	v_cvt_pk_bf16_f32 v135, v161, v185
	global_store_short v[174:175], v135, off offset:3584
	global_store_dwordx4 v[172:173], v[130:133], off nt
	global_store_dwordx4 v[172:173], v[158:161], off offset:16 nt
	s_nop 0
	v_pk_mul_f32 v[132:133], v[86:87], v[134:135] op_sel_hi:[1,0]
	v_pk_mul_f32 v[130:131], v[84:85], v[134:135] op_sel_hi:[1,0]
	v_pk_mul_f32 v[160:161], v[82:83], v[134:135] op_sel_hi:[1,0]
	v_pk_mul_f32 v[158:159], v[80:81], v[134:135] op_sel_hi:[1,0]
	v_lshl_add_u64 v[134:135], v[170:171], 0, v[156:157]
	v_cvt_pk_bf16_f32 v170, v130, v185
	global_store_short v[134:135], v170, off
	v_cvt_pk_bf16_f32 v170, v158, v185
	global_store_short v[134:135], v170, off offset:2048
	v_cvt_pk_bf16_f32 v170, v131, v185
	global_store_short v[134:135], v170, off offset:512
	v_cvt_pk_bf16_f32 v170, v159, v185
	global_store_short v[134:135], v170, off offset:2560
	v_cvt_pk_bf16_f32 v170, v132, v185
	global_store_short v[134:135], v170, off offset:1024
	v_cvt_pk_bf16_f32 v170, v160, v185
	global_store_short v[134:135], v170, off offset:3072
	v_cvt_pk_bf16_f32 v170, v133, v185
	global_store_short v[134:135], v170, off offset:1536
	v_cvt_pk_bf16_f32 v170, v161, v185
	global_store_short v[134:135], v170, off offset:3584
	global_store_dwordx4 v[172:173], v[130:133], off offset:128 nt
	global_store_dwordx4 v[172:173], v[158:161], off offset:144 nt
	s_nop 0
	v_mov_b32_e32 v130, v163
	s_nop 0
	v_mov_b32_e32 v134, v217
	v_ashrrev_i32_e32 v131, 31, v130
	v_lshl_add_u64 v[170:171], v[130:131], 1, s[22:23]
	v_lshlrev_b64 v[130:131], 10, v[130:131]
	v_lshl_add_u64 v[172:173], s[0:1], 0, v[130:131]
	v_lshl_add_u64 v[174:175], v[170:171], 0, v[128:129]
	v_lshl_add_u64 v[172:173], v[172:173], 0, v[154:155]
	v_pk_mul_f32 v[132:133], v[78:79], v[134:135] op_sel_hi:[1,0]
	v_pk_mul_f32 v[130:131], v[76:77], v[134:135] op_sel_hi:[1,0]
	v_pk_mul_f32 v[160:161], v[74:75], v[134:135] op_sel_hi:[1,0]
	v_pk_mul_f32 v[158:159], v[72:73], v[134:135] op_sel_hi:[1,0]
	v_cvt_pk_bf16_f32 v135, v130, v185
	global_store_short v[174:175], v135, off
	v_cvt_pk_bf16_f32 v135, v158, v185
	global_store_short v[174:175], v135, off offset:2048
	v_cvt_pk_bf16_f32 v135, v131, v185
	global_store_short v[174:175], v135, off offset:512
	v_cvt_pk_bf16_f32 v135, v159, v185
	global_store_short v[174:175], v135, off offset:2560
	v_cvt_pk_bf16_f32 v135, v132, v185
	global_store_short v[174:175], v135, off offset:1024
	v_cvt_pk_bf16_f32 v135, v160, v185
	global_store_short v[174:175], v135, off offset:3072
	v_cvt_pk_bf16_f32 v135, v133, v185
	global_store_short v[174:175], v135, off offset:1536
	v_cvt_pk_bf16_f32 v135, v161, v185
	global_store_short v[174:175], v135, off offset:3584
	global_store_dwordx4 v[172:173], v[130:133], off nt
	global_store_dwordx4 v[172:173], v[158:161], off offset:16 nt
	s_nop 0
	v_pk_mul_f32 v[132:133], v[70:71], v[134:135] op_sel_hi:[1,0]
	v_pk_mul_f32 v[130:131], v[68:69], v[134:135] op_sel_hi:[1,0]
	v_pk_mul_f32 v[160:161], v[66:67], v[134:135] op_sel_hi:[1,0]
	v_pk_mul_f32 v[158:159], v[64:65], v[134:135] op_sel_hi:[1,0]
	v_lshl_add_u64 v[134:135], v[170:171], 0, v[156:157]
	v_cvt_pk_bf16_f32 v170, v130, v185
	global_store_short v[134:135], v170, off
	v_cvt_pk_bf16_f32 v170, v158, v185
	global_store_short v[134:135], v170, off offset:2048
	v_cvt_pk_bf16_f32 v170, v131, v185
	global_store_short v[134:135], v170, off offset:512
	v_cvt_pk_bf16_f32 v170, v159, v185
	global_store_short v[134:135], v170, off offset:2560
	v_cvt_pk_bf16_f32 v170, v132, v185
	global_store_short v[134:135], v170, off offset:1024
	v_cvt_pk_bf16_f32 v170, v160, v185
	global_store_short v[134:135], v170, off offset:3072
	v_cvt_pk_bf16_f32 v170, v133, v185
	global_store_short v[134:135], v170, off offset:1536
	v_cvt_pk_bf16_f32 v170, v161, v185
	global_store_short v[134:135], v170, off offset:3584
	global_store_dwordx4 v[172:173], v[130:133], off offset:128 nt
	global_store_dwordx4 v[172:173], v[158:161], off offset:144 nt
	s_nop 0
	v_mov_b32_e32 v130, v164
	s_nop 0
	v_mov_b32_e32 v134, v220
	v_ashrrev_i32_e32 v131, 31, v130
	v_lshl_add_u64 v[170:171], v[130:131], 1, s[22:23]
	v_lshlrev_b64 v[130:131], 10, v[130:131]
	v_lshl_add_u64 v[172:173], s[0:1], 0, v[130:131]
	v_lshl_add_u64 v[174:175], v[170:171], 0, v[128:129]
	v_lshl_add_u64 v[172:173], v[172:173], 0, v[154:155]
	v_pk_mul_f32 v[132:133], v[62:63], v[134:135] op_sel_hi:[1,0]
	v_pk_mul_f32 v[130:131], v[60:61], v[134:135] op_sel_hi:[1,0]
	v_pk_mul_f32 v[160:161], v[58:59], v[134:135] op_sel_hi:[1,0]
	v_pk_mul_f32 v[158:159], v[56:57], v[134:135] op_sel_hi:[1,0]
	v_cvt_pk_bf16_f32 v135, v130, v185
	global_store_short v[174:175], v135, off
	v_cvt_pk_bf16_f32 v135, v158, v185
	global_store_short v[174:175], v135, off offset:2048
	v_cvt_pk_bf16_f32 v135, v131, v185
	global_store_short v[174:175], v135, off offset:512
	v_cvt_pk_bf16_f32 v135, v159, v185
	global_store_short v[174:175], v135, off offset:2560
	v_cvt_pk_bf16_f32 v135, v132, v185
	global_store_short v[174:175], v135, off offset:1024
	v_cvt_pk_bf16_f32 v135, v160, v185
	global_store_short v[174:175], v135, off offset:3072
	v_cvt_pk_bf16_f32 v135, v133, v185
; __device__ __forceinline__ bf16_t f2bf1(float f) { return (bf16_t)(cvt_pk_bf16(f, 0.f) & 0xffffu); }
;     __device__ __forceinline__ void operator()(const f32x4 (&acc)[2][2][4][2], const Unit& u, int wr, int wc, int fr, int fq) const {
;     ...
;             for (int ai = 0; ai < 2; ++ai)
; #pragma unroll
;                 for (int m = 0; m < 4; ++m) {
;                     int mrow = ai * HALF + wr * 64 + m * 16 + fr;
;                     asm volatile("" : "+v"(mrow));
;                     const float rs = MRS[b * 256 + mrow];
; #pragma unroll
;                     for (int bj = 0; bj < 2; ++bj) {
;                         const f32x4 v0 = acc[ai][bj][m][0] * rs, v1 = acc[ai][bj][m][1] * rs;
;                         const int c0 = wc * 64 + bj * 32 + 8 * fq;
;                         bf16_t* vp = MVT + ((size_t)(l * 40 + b) * 256 + c0) * 256 + mrow;
; #pragma unroll
;                         for (int j = 0; j < 4; ++j) { vp[j * 256] = f2bf1(v0[j]); vp[(4 + j) * 256] = f2bf1(v1[j]); }
;                         float* d = o_mv + ((size_t)(l * 8 + b) * 256 + mrow) * 256 + c0; __builtin_nontemporal_store(v0, (f32x4*)d); __builtin_nontemporal_store(v1, (f32x4*)(d + 4));
;                     }
	global_store_short v[174:175], v135, off offset:1536
	v_cvt_pk_bf16_f32 v135, v161, v185
	global_store_short v[174:175], v135, off offset:3584
	global_store_dwordx4 v[172:173], v[130:133], off nt
	global_store_dwordx4 v[172:173], v[158:161], off offset:16 nt
	s_nop 0
	v_pk_mul_f32 v[132:133], v[54:55], v[134:135] op_sel_hi:[1,0]
	v_pk_mul_f32 v[130:131], v[52:53], v[134:135] op_sel_hi:[1,0]
	v_pk_mul_f32 v[160:161], v[50:51], v[134:135] op_sel_hi:[1,0]
	v_pk_mul_f32 v[158:159], v[48:49], v[134:135] op_sel_hi:[1,0]
	v_lshl_add_u64 v[134:135], v[170:171], 0, v[156:157]
	v_cvt_pk_bf16_f32 v170, v130, v185
	global_store_short v[134:135], v170, off
	v_cvt_pk_bf16_f32 v170, v158, v185
	global_store_short v[134:135], v170, off offset:2048
	v_cvt_pk_bf16_f32 v170, v131, v185
	global_store_short v[134:135], v170, off offset:512
	v_cvt_pk_bf16_f32 v170, v159, v185
	global_store_short v[134:135], v170, off offset:2560
	v_cvt_pk_bf16_f32 v170, v132, v185
	global_store_short v[134:135], v170, off offset:1024
	v_cvt_pk_bf16_f32 v170, v160, v185
	global_store_short v[134:135], v170, off offset:3072
	v_cvt_pk_bf16_f32 v170, v133, v185
	global_store_short v[134:135], v170, off offset:1536
	v_cvt_pk_bf16_f32 v170, v161, v185
	global_store_short v[134:135], v170, off offset:3584
	global_store_dwordx4 v[172:173], v[130:133], off offset:128 nt
	global_store_dwordx4 v[172:173], v[158:161], off offset:144 nt
	s_nop 0
	v_mov_b32_e32 v130, v165
	s_nop 0
	v_mov_b32_e32 v134, v223
	v_ashrrev_i32_e32 v131, 31, v130
	v_lshl_add_u64 v[170:171], v[130:131], 1, s[22:23]
	v_lshlrev_b64 v[130:131], 10, v[130:131]
	v_lshl_add_u64 v[172:173], s[0:1], 0, v[130:131]
	v_lshl_add_u64 v[174:175], v[170:171], 0, v[128:129]
	v_lshl_add_u64 v[172:173], v[172:173], 0, v[154:155]
	v_pk_mul_f32 v[132:133], v[46:47], v[134:135] op_sel_hi:[1,0]
	v_pk_mul_f32 v[130:131], v[44:45], v[134:135] op_sel_hi:[1,0]
	v_pk_mul_f32 v[160:161], v[42:43], v[134:135] op_sel_hi:[1,0]
	v_pk_mul_f32 v[158:159], v[40:41], v[134:135] op_sel_hi:[1,0]
	v_cvt_pk_bf16_f32 v135, v130, v185
	global_store_short v[174:175], v135, off
	v_cvt_pk_bf16_f32 v135, v158, v185
	global_store_short v[174:175], v135, off offset:2048
	v_cvt_pk_bf16_f32 v135, v131, v185
	global_store_short v[174:175], v135, off offset:512
	v_cvt_pk_bf16_f32 v135, v159, v185
	global_store_short v[174:175], v135, off offset:2560
	v_cvt_pk_bf16_f32 v135, v132, v185
	global_store_short v[174:175], v135, off offset:1024
	v_cvt_pk_bf16_f32 v135, v160, v185
	global_store_short v[174:175], v135, off offset:3072
	v_cvt_pk_bf16_f32 v135, v133, v185
	global_store_short v[174:175], v135, off offset:1536
	v_cvt_pk_bf16_f32 v135, v161, v185
	global_store_short v[174:175], v135, off offset:3584
	global_store_dwordx4 v[172:173], v[130:133], off nt
	global_store_dwordx4 v[172:173], v[158:161], off offset:16 nt
	s_nop 0
	v_pk_mul_f32 v[132:133], v[38:39], v[134:135] op_sel_hi:[1,0]
	v_pk_mul_f32 v[130:131], v[36:37], v[134:135] op_sel_hi:[1,0]
	v_pk_mul_f32 v[160:161], v[34:35], v[134:135] op_sel_hi:[1,0]
	v_pk_mul_f32 v[158:159], v[32:33], v[134:135] op_sel_hi:[1,0]
	v_lshl_add_u64 v[134:135], v[170:171], 0, v[156:157]
	v_cvt_pk_bf16_f32 v170, v130, v185
	global_store_short v[134:135], v170, off
	v_cvt_pk_bf16_f32 v170, v158, v185
	global_store_short v[134:135], v170, off offset:2048
	v_cvt_pk_bf16_f32 v170, v131, v185
	global_store_short v[134:135], v170, off offset:512
	v_cvt_pk_bf16_f32 v170, v159, v185
	global_store_short v[134:135], v170, off offset:2560
	v_cvt_pk_bf16_f32 v170, v132, v185
	global_store_short v[134:135], v170, off offset:1024
	v_cvt_pk_bf16_f32 v170, v160, v185
	global_store_short v[134:135], v170, off offset:3072
	v_cvt_pk_bf16_f32 v170, v133, v185
	global_store_short v[134:135], v170, off offset:1536
	v_cvt_pk_bf16_f32 v170, v161, v185
	global_store_short v[134:135], v170, off offset:3584
	global_store_dwordx4 v[172:173], v[130:133], off offset:128 nt
	global_store_dwordx4 v[172:173], v[158:161], off offset:144 nt
	s_nop 0
	v_mov_b32_e32 v130, v166
	s_nop 0
	v_mov_b32_e32 v134, v226
	v_ashrrev_i32_e32 v131, 31, v130
	v_lshl_add_u64 v[170:171], v[130:131], 1, s[22:23]
	v_lshlrev_b64 v[130:131], 10, v[130:131]
	v_lshl_add_u64 v[172:173], s[0:1], 0, v[130:131]
	v_lshl_add_u64 v[174:175], v[170:171], 0, v[128:129]
	v_lshl_add_u64 v[172:173], v[172:173], 0, v[154:155]
	v_pk_mul_f32 v[132:133], v[30:31], v[134:135] op_sel_hi:[1,0]
	v_pk_mul_f32 v[130:131], v[28:29], v[134:135] op_sel_hi:[1,0]
	v_pk_mul_f32 v[160:161], v[26:27], v[134:135] op_sel_hi:[1,0]
	v_pk_mul_f32 v[158:159], v[24:25], v[134:135] op_sel_hi:[1,0]
; __device__ __forceinline__ bf16_t f2bf1(float f) { return (bf16_t)(cvt_pk_bf16(f, 0.f) & 0xffffu); }
;     __device__ __forceinline__ void operator()(const f32x4 (&acc)[2][2][4][2], const Unit& u, int wr, int wc, int fr, int fq) const {
;     ...
;             for (int ai = 0; ai < 2; ++ai)
; #pragma unroll
;                 for (int m = 0; m < 4; ++m) {
;                     int mrow = ai * HALF + wr * 64 + m * 16 + fr;
;                     asm volatile("" : "+v"(mrow));
;                     const float rs = MRS[b * 256 + mrow];
; #pragma unroll
;                     for (int bj = 0; bj < 2; ++bj) {
;                         const f32x4 v0 = acc[ai][bj][m][0] * rs, v1 = acc[ai][bj][m][1] * rs;
;                         const int c0 = wc * 64 + bj * 32 + 8 * fq;
;                         bf16_t* vp = MVT + ((size_t)(l * 40 + b) * 256 + c0) * 256 + mrow;
; #pragma unroll
;                         for (int j = 0; j < 4; ++j) { vp[j * 256] = f2bf1(v0[j]); vp[(4 + j) * 256] = f2bf1(v1[j]); }
;                         float* d = o_mv + ((size_t)(l * 8 + b) * 256 + mrow) * 256 + c0; __builtin_nontemporal_store(v0, (f32x4*)d); __builtin_nontemporal_store(v1, (f32x4*)(d + 4));
;                     }
	v_cvt_pk_bf16_f32 v135, v130, v185
	global_store_short v[174:175], v135, off
	v_cvt_pk_bf16_f32 v135, v158, v185
	global_store_short v[174:175], v135, off offset:2048
	v_cvt_pk_bf16_f32 v135, v131, v185
	global_store_short v[174:175], v135, off offset:512
	v_cvt_pk_bf16_f32 v135, v159, v185
	global_store_short v[174:175], v135, off offset:2560
	v_cvt_pk_bf16_f32 v135, v132, v185
	global_store_short v[174:175], v135, off offset:1024
	v_cvt_pk_bf16_f32 v135, v160, v185
	global_store_short v[174:175], v135, off offset:3072
	v_cvt_pk_bf16_f32 v135, v133, v185
	global_store_short v[174:175], v135, off offset:1536
	v_cvt_pk_bf16_f32 v135, v161, v185
	global_store_short v[174:175], v135, off offset:3584
	global_store_dwordx4 v[172:173], v[130:133], off nt
	global_store_dwordx4 v[172:173], v[158:161], off offset:16 nt
	s_nop 0
	v_pk_mul_f32 v[132:133], v[22:23], v[134:135] op_sel_hi:[1,0]
	v_pk_mul_f32 v[130:131], v[20:21], v[134:135] op_sel_hi:[1,0]
	v_pk_mul_f32 v[160:161], v[18:19], v[134:135] op_sel_hi:[1,0]
	v_pk_mul_f32 v[158:159], v[16:17], v[134:135] op_sel_hi:[1,0]
	v_lshl_add_u64 v[134:135], v[170:171], 0, v[156:157]
	v_cvt_pk_bf16_f32 v170, v130, v185
	global_store_short v[134:135], v170, off
	v_cvt_pk_bf16_f32 v170, v158, v185
	global_store_short v[134:135], v170, off offset:2048
	v_cvt_pk_bf16_f32 v170, v131, v185
	global_store_short v[134:135], v170, off offset:512
	v_cvt_pk_bf16_f32 v170, v159, v185
	global_store_short v[134:135], v170, off offset:2560
	v_cvt_pk_bf16_f32 v170, v132, v185
	global_store_short v[134:135], v170, off offset:1024
	v_cvt_pk_bf16_f32 v170, v160, v185
	global_store_short v[134:135], v170, off offset:3072
	v_cvt_pk_bf16_f32 v170, v133, v185
	global_store_short v[134:135], v170, off offset:1536
	v_cvt_pk_bf16_f32 v170, v161, v185
	global_store_short v[134:135], v170, off offset:3584
	global_store_dwordx4 v[172:173], v[130:133], off offset:128 nt
	global_store_dwordx4 v[172:173], v[158:161], off offset:144 nt
	s_nop 0
	v_mov_b32_e32 v130, v167
	s_nop 0
	v_mov_b32_e32 v160, v250
	v_ashrrev_i32_e32 v131, 31, v130
	v_lshl_add_u64 v[174:175], v[130:131], 1, s[22:23]
	v_lshlrev_b64 v[130:131], 10, v[130:131]
	v_lshl_add_u64 v[134:135], s[0:1], 0, v[130:131]
	v_lshl_add_u64 v[128:129], v[174:175], 0, v[128:129]
	v_lshl_add_u64 v[156:157], v[174:175], 0, v[156:157]
	v_pk_mul_f32 v[130:131], v[12:13], v[160:161] op_sel_hi:[1,0]
	s_nop 0
	v_cvt_pk_bf16_f32 v158, v130, v185
	v_pk_mul_f32 v[170:171], v[8:9], v[160:161] op_sel_hi:[1,0]
	global_store_short v[128:129], v158, off
	v_cvt_pk_bf16_f32 v158, v170, v185
	global_store_short v[128:129], v158, off offset:2048
	v_cvt_pk_bf16_f32 v158, v131, v185
	global_store_short v[128:129], v158, off offset:512
	v_cvt_pk_bf16_f32 v158, v171, v185
	v_pk_mul_f32 v[132:133], v[14:15], v[160:161] op_sel_hi:[1,0]
	global_store_short v[128:129], v158, off offset:2560
	v_cvt_pk_bf16_f32 v158, v132, v185
	v_pk_mul_f32 v[172:173], v[10:11], v[160:161] op_sel_hi:[1,0]
	global_store_short v[128:129], v158, off offset:1024
	v_cvt_pk_bf16_f32 v158, v172, v185
	global_store_short v[128:129], v158, off offset:3072
	v_cvt_pk_bf16_f32 v158, v133, v185
	global_store_short v[128:129], v158, off offset:1536
	v_cvt_pk_bf16_f32 v158, v173, v185
	global_store_short v[128:129], v158, off offset:3584
	v_lshl_add_u64 v[158:159], v[134:135], 0, v[154:155]
	global_store_dwordx4 v[158:159], v[130:133], off nt
	global_store_dwordx4 v[158:159], v[170:173], off offset:16 nt
	v_pk_mul_f32 v[128:129], v[0:1], v[160:161] op_sel_hi:[1,0]
	v_pk_mul_f32 v[132:133], v[4:5], v[160:161] op_sel_hi:[1,0]
	v_pk_mul_f32 v[134:135], v[6:7], v[160:161] op_sel_hi:[1,0]
	v_cvt_pk_bf16_f32 v155, v132, v185
	global_store_short v[156:157], v155, off
	v_cvt_pk_bf16_f32 v155, v128, v185
	global_store_short v[156:157], v155, off offset:2048
	v_cvt_pk_bf16_f32 v155, v133, v185
	global_store_short v[156:157], v155, off offset:512
	v_cvt_pk_bf16_f32 v155, v129, v185
	global_store_short v[156:157], v155, off offset:2560
	v_cvt_pk_bf16_f32 v155, v134, v185
	v_pk_mul_f32 v[130:131], v[2:3], v[160:161] op_sel_hi:[1,0]
	global_store_short v[156:157], v155, off offset:1024
	v_cvt_pk_bf16_f32 v155, v130, v185
	global_store_short v[156:157], v155, off offset:3072
	v_cvt_pk_bf16_f32 v155, v135, v185
	global_store_short v[156:157], v155, off offset:1536
	v_cvt_pk_bf16_f32 v155, v131, v185
	global_store_short v[156:157], v155, off offset:3584
	v_lshl_add_u64 v[156:157], v[158:159], 0, s[96:97]
	global_store_dwordx4 v[158:159], v[132:135], off offset:128 nt
	s_cbranch_execz .LBB0_516

; __device__ __forceinline__ float quad_sum(float s) { s += __shfl_xor(s, 16); s += __shfl_xor(s, 32); return s; }
; __device__ __forceinline__ float sq4(const f32x4 a) { return (a[0] * a[0] + a[1] * a[1]) + (a[2] * a[2] + a[3] * a[3]); }
; __device__ __forceinline__ u32x4 pack8(const f32x4 a, const f32x4 b) { u32x4 w; w.x = cvt_pk_bf16(a[0], a[1]); w.y = cvt_pk_bf16(a[2], a[3]); w.z = cvt_pk_bf16(b[0], b[1]); w.w = cvt_pk_bf16(b[2], b[3]); return w; }
;     __device__ __forceinline__ void operator()(const f32x4 (&acc)[2][2][4][2], const Unit& u, int wr, int wc, int fr, int fq) const {
;     ...
;             bf16_t* MK = (bf16_t*)(ws + WS_MK); float* o_mk = out + O_MKP;
;             const float* g = (const float*)(ws + WS_GT) + l * 256 + 192;
; #pragma unroll
;             for (int ai = 0; ai < 2; ++ai)
; #pragma unroll
;                 for (int m = 0; m < 4; ++m) {
;                     int mrow = ai * HALF + wr * 64 + m * 16 + fr;
;                     asm volatile("" : "+v"(mrow));
;                     const float rs = MRS[b * 256 + mrow];
;                     f32x4 v[2][2];
; #pragma unroll
;                     for (int bj = 0; bj < 2; ++bj)
; #pragma unroll
;                         for (int n = 0; n < 2; ++n) v[bj][n] = acc[ai][bj][m][n] * rs;
;                     float ss = (sq4(v[0][0]) + sq4(v[0][1])) + (sq4(v[1][0]) + sq4(v[1][1]));
;                     ss = quad_sum(ss);
;                     const float hr = 1.0f / sqrtf(ss * (1.0f / 64.0f) + E_EPS);
; #pragma unroll
;                     for (int bj = 0; bj < 2; ++bj) {
;                         const int c0 = bj * 32 + 8 * fq;
;                         const f32x4 g0 = *(const f32x4*)(g + c0), g1 = *(const f32x4*)(g + c0 + 4);
;                         const f32x4 o0 = v[bj][0] * hr * g0, o1 = v[bj][1] * hr * g1;
;                         *(u32x4*)(MK + ((size_t)(l * 40 + b) * 256 + mrow) * 256 + wc * 64 + c0) = pack8(o0, o1);
.LBB0_516:
	s_lshl_b32 s0, s4, 8
	s_ashr_i32 s1, s0, 31
	s_lshl_b64 s[0:1], s[0:1], 2
	s_add_u32 s0, s48, s0
	s_addc_u32 s1, s49, s1
	s_add_u32 s40, s0, 0x8510300
	s_addc_u32 s41, s1, 0
	s_lshl_b32 s2, s14, 8
	v_mov_b32_e32 v156, v145
	s_add_i32 s0, s5, s14
	v_add_u32_e32 v128, s2, v156
	v_ashrrev_i32_e32 v129, 31, v128
	v_lshl_add_u64 v[128:129], v[128:129], 2, s[20:21]
	global_load_dword v130, v[128:129], off
	v_add_u32_e32 v128, s2, v149
	v_ashrrev_i32_e32 v129, 31, v128
	v_lshl_add_u64 v[128:129], v[128:129], 2, s[20:21]
	global_load_dword v190, v[128:129], off
	v_add_u32_e32 v128, s2, v162
	v_ashrrev_i32_e32 v129, 31, v128
	v_lshl_add_u64 v[128:129], v[128:129], 2, s[20:21]
	global_load_dword v191, v[128:129], off
	v_add_u32_e32 v128, s2, v163
	v_ashrrev_i32_e32 v129, 31, v128
	v_lshl_add_u64 v[128:129], v[128:129], 2, s[20:21]
	global_load_dword v217, v[128:129], off
	v_add_u32_e32 v128, s2, v164
	v_ashrrev_i32_e32 v129, 31, v128
	v_lshl_add_u64 v[128:129], v[128:129], 2, s[20:21]
	global_load_dword v220, v[128:129], off
	v_add_u32_e32 v128, s2, v165
	v_ashrrev_i32_e32 v129, 31, v128
	v_lshl_add_u64 v[128:129], v[128:129], 2, s[20:21]
	global_load_dword v223, v[128:129], off
	v_add_u32_e32 v128, s2, v166
	v_ashrrev_i32_e32 v129, 31, v128
	v_lshl_add_u64 v[128:129], v[128:129], 2, s[20:21]
	global_load_dword v226, v[128:129], off
	v_add_u32_e32 v128, s2, v167
	v_ashrrev_i32_e32 v129, 31, v128
	v_lshl_add_u64 v[128:129], v[128:129], 2, s[20:21]
	global_load_dword v250, v[128:129], off
	s_mov_b32 s3, 0xf800000
	s_ashr_i32 s1, s0, 31
	s_lshl_b64 s[8:9], s[0:1], 17
	s_add_u32 s14, s47, s8
	s_addc_u32 s15, s93, s9
	s_lshl_b32 s1, s4, 5
	s_sub_i32 s0, s0, s1
	s_ashr_i32 s1, s0, 31
	s_lshl_b64 s[0:1], s[0:1], 18
	s_add_u32 s24, s94, s0
	s_addc_u32 s25, s95, s1
	v_ashrrev_i32_e32 v157, 31, v156
	v_lshlrev_b32_e32 v184, 2, v144
	s_waitcnt vmcnt(0)
	v_pk_mul_f32 v[124:125], v[124:125], v[130:131] op_sel_hi:[1,0]
	v_pk_mul_f32 v[132:133], v[116:117], v[130:131] op_sel_hi:[1,0]
	v_pk_mul_f32 v[160:161], v[126:127], v[130:131] op_sel_hi:[1,0]
	v_pk_mul_f32 v[128:129], v[118:119], v[130:131] op_sel_hi:[1,0]
	v_pk_mul_f32 v[126:127], v[114:115], v[130:131] op_sel_hi:[1,0]
	v_mov_b32_e32 v114, v125
	v_mov_b32_e32 v115, v133
	v_pk_mul_f32 v[122:123], v[122:123], v[130:131] op_sel_hi:[1,0]
	v_pk_mul_f32 v[120:121], v[120:121], v[130:131] op_sel_hi:[1,0]
	v_pk_mul_f32 v[130:131], v[112:113], v[130:131] op_sel_hi:[1,0]
	v_mov_b32_e32 v112, v124
	v_mov_b32_e32 v113, v132
	v_pk_mul_f32 v[114:115], v[114:115], v[114:115]
	v_mov_b32_e32 v116, v161
	v_mov_b32_e32 v117, v129
	v_pk_fma_f32 v[112:113], v[112:113], v[112:113], v[114:115]
	v_mov_b32_e32 v114, v160
	v_mov_b32_e32 v115, v128
	v_pk_mul_f32 v[116:117], v[116:117], v[116:117]
	v_mov_b32_e32 v118, v123
	v_pk_fma_f32 v[114:115], v[114:115], v[114:115], v[116:117]
	v_mov_b32_e32 v116, v121
	v_mov_b32_e32 v117, v131
	v_pk_add_f32 v[112:113], v[112:113], v[114:115]
	v_mov_b32_e32 v114, v120
	v_mov_b32_e32 v115, v130
	v_pk_mul_f32 v[116:117], v[116:117], v[116:117]
	v_mov_b32_e32 v119, v127
	v_pk_fma_f32 v[114:115], v[114:115], v[114:115], v[116:117]
	v_mov_b32_e32 v116, v122
	v_mov_b32_e32 v117, v126
	v_pk_mul_f32 v[118:119], v[118:119], v[118:119]
	s_nop 0
	v_pk_fma_f32 v[116:117], v[116:117], v[116:117], v[118:119]
	s_nop 0
	v_pk_add_f32 v[114:115], v[114:115], v[116:117]
	s_nop 0
	v_pk_add_f32 v[112:113], v[112:113], v[114:115]
	v_and_b32_e32 v114, 64, v222
	v_add_f32_e32 v112, v112, v113
	v_xor_b32_e32 v113, 16, v222
	v_add_u32_e32 v114, 64, v114
	v_cmp_lt_i32_e32 vcc, v113, v114
	s_nop 1
	v_cndmask_b32_e32 v113, v222, v113, vcc
	v_lshlrev_b32_e32 v135, 2, v113
	ds_bpermute_b32 v113, v135, v112
	s_waitcnt lgkmcnt(0)
	v_add_f32_e32 v112, v112, v113
	v_xor_b32_e32 v113, 32, v222
	v_cmp_lt_i32_e32 vcc, v113, v114
	s_nop 1
	v_cndmask_b32_e32 v113, v222, v113, vcc
	v_lshlrev_b32_e32 v155, 2, v113
	ds_bpermute_b32 v113, v155, v112
	s_waitcnt lgkmcnt(0)
	v_add_f32_e32 v112, v112, v113
	v_fmamk_f32 v112, v112, 0x3c800000, v218
	v_cmp_gt_f32_e32 vcc, s3, v112
	v_mul_f32_e32 v113, 0x4f800000, v112
	s_nop 0
	v_cndmask_b32_e32 v112, v112, v113, vcc
	v_sqrt_f32_e32 v113, v112
	s_nop 0
	v_add_u32_e32 v114, -1, v113
	v_fma_f32 v115, -v114, v113, v112
	v_cmp_ge_f32_e64 s[0:1], 0, v115
	v_add_u32_e32 v115, 1, v113
	s_nop 0
	v_cndmask_b32_e64 v114, v113, v114, s[0:1]
	v_fma_f32 v113, -v115, v113, v112
	v_cmp_lt_f32_e64 s[0:1], 0, v113
	s_nop 1
	v_cndmask_b32_e64 v113, v114, v115, s[0:1]
	v_mul_f32_e32 v114, 0x37800000, v113
	v_cndmask_b32_e32 v113, v113, v114, vcc
	v_cmp_class_f32_e32 vcc, v112, v219
	s_nop 1
	v_cndmask_b32_e32 v112, v113, v112, vcc
	v_div_scale_f32 v113, s[0:1], v112, v112, 1.0
	v_rcp_f32_e32 v114, v113
	s_nop 0
	v_fma_f32 v115, -v113, v114, 1.0
	v_fmac_f32_e32 v114, v115, v114
	v_div_scale_f32 v115, vcc, 1.0, v112, 1.0
	v_mul_f32_e32 v116, v115, v114
	v_fma_f32 v117, -v113, v116, v115
	v_fmac_f32_e32 v116, v117, v114
	v_fma_f32 v113, -v113, v116, v115
	v_div_fmas_f32 v113, v113, v114, v116
	v_div_fixup_f32 v134, v113, v112, 1.0
	v_lshlrev_b64 v[112:113], 9, v[156:157]
	v_lshl_add_u64 v[158:159], s[14:15], 0, v[112:113]
	v_lshlrev_b64 v[112:113], 10, v[156:157]
	v_lshl_add_u64 v[156:157], s[24:25], 0, v[112:113]
	global_load_dwordx4 v[112:115], v184, s[40:41] offset:16
	global_load_dwordx4 v[116:119], v184, s[40:41]
	v_pk_mul_f32 v[124:125], v[124:125], v[134:135] op_sel_hi:[1,0]
	v_pk_mul_f32 v[160:161], v[160:161], v[134:135] op_sel_hi:[1,0]
	v_pk_mul_f32 v[120:121], v[120:121], v[134:135] op_sel_hi:[1,0]
	v_pk_mul_f32 v[122:123], v[122:123], v[134:135] op_sel_hi:[1,0]
	v_lshl_add_u64 v[156:157], v[156:157], 0, v[184:185]
	s_waitcnt vmcnt(1)
; __device__ __forceinline__ float quad_sum(float s) { s += __shfl_xor(s, 16); s += __shfl_xor(s, 32); return s; }
; __device__ __forceinline__ float sq4(const f32x4 a) { return (a[0] * a[0] + a[1] * a[1]) + (a[2] * a[2] + a[3] * a[3]); }
; __device__ __forceinline__ u32x4 pack8(const f32x4 a, const f32x4 b) { u32x4 w; w.x = cvt_pk_bf16(a[0], a[1]); w.y = cvt_pk_bf16(a[2], a[3]); w.z = cvt_pk_bf16(b[0], b[1]); w.w = cvt_pk_bf16(b[2], b[3]); return w; }
;     __device__ __forceinline__ void operator()(const f32x4 (&acc)[2][2][4][2], const Unit& u, int wr, int wc, int fr, int fq) const {
;     ...
;                     int mrow = ai * HALF + wr * 64 + m * 16 + fr;
;                     asm volatile("" : "+v"(mrow));
;                     const float rs = MRS[b * 256 + mrow];
;                     f32x4 v[2][2];
; #pragma unroll
;                     for (int bj = 0; bj < 2; ++bj)
; #pragma unroll
;                         for (int n = 0; n < 2; ++n) v[bj][n] = acc[ai][bj][m][n] * rs;
;                     float ss = (sq4(v[0][0]) + sq4(v[0][1])) + (sq4(v[1][0]) + sq4(v[1][1]));
;                     ss = quad_sum(ss);
;                     const float hr = 1.0f / sqrtf(ss * (1.0f / 64.0f) + E_EPS);
; #pragma unroll
;                     for (int bj = 0; bj < 2; ++bj) {
;                         const int c0 = bj * 32 + 8 * fq;
;                         const f32x4 g0 = *(const f32x4*)(g + c0), g1 = *(const f32x4*)(g + c0 + 4);
;                         const f32x4 o0 = v[bj][0] * hr * g0, o1 = v[bj][1] * hr * g1;
;                         *(u32x4*)(MK + ((size_t)(l * 40 + b) * 256 + mrow) * 256 + wc * 64 + c0) = pack8(o0, o1);
;                         float* d = o_mk + ((size_t)(l * 8 + b) * 256 + mrow) * 256 + wc * 64 + c0; __builtin_nontemporal_store(o0, (f32x4*)d); __builtin_nontemporal_store(o1, (f32x4*)(d + 4));
;                     }
	v_pk_mul_f32 v[114:115], v[114:115], v[122:123]
	s_waitcnt vmcnt(0)
	v_pk_mul_f32 v[116:117], v[116:117], v[124:125]
	v_lshlrev_b32_e32 v124, 1, v144
	v_mov_b32_e32 v125, v185
	v_pk_mul_f32 v[118:119], v[118:119], v[160:161]
	v_lshl_add_u64 v[158:159], v[158:159], 0, v[124:125]
	v_pk_mul_f32 v[112:113], v[112:113], v[120:121]
	v_cvt_pk_bf16_f32 v120, v116, v117
	v_cvt_pk_bf16_f32 v121, v118, v119
	s_nop 0
	v_cvt_pk_bf16_f32 v122, v112, v113
	v_cvt_pk_bf16_f32 v123, v114, v115
	global_store_dwordx4 v[158:159], v[120:123], off
	global_store_dwordx4 v[156:157], v[116:119], off nt
	global_store_dwordx4 v[156:157], v[112:115], off offset:16 nt
	global_load_dwordx4 v[112:115], v169, s[40:41] offset:16
	s_nop 0
	global_load_dwordx4 v[116:119], v169, s[40:41]
	v_pk_mul_f32 v[120:121], v[132:133], v[134:135] op_sel_hi:[1,0]
	v_pk_mul_f32 v[122:123], v[128:129], v[134:135] op_sel_hi:[1,0]
	s_waitcnt vmcnt(0)
	v_pk_mul_f32 v[116:117], v[116:117], v[120:121]
	v_pk_mul_f32 v[118:119], v[118:119], v[122:123]
	v_pk_mul_f32 v[120:121], v[130:131], v[134:135] op_sel_hi:[1,0]
	v_pk_mul_f32 v[122:123], v[126:127], v[134:135] op_sel_hi:[1,0]
	v_pk_mul_f32 v[112:113], v[112:113], v[120:121]
	v_pk_mul_f32 v[114:115], v[114:115], v[122:123]
	v_cvt_pk_bf16_f32 v120, v116, v117
	v_cvt_pk_bf16_f32 v121, v118, v119
	v_cvt_pk_bf16_f32 v122, v112, v113
	s_nop 0
	v_cvt_pk_bf16_f32 v123, v114, v115
	global_store_dwordx4 v[158:159], v[120:123], off offset:64
	global_store_dwordx4 v[156:157], v[116:119], off offset:128 nt
	global_store_dwordx4 v[156:157], v[112:115], off offset:144 nt
	s_nop 0
	v_mov_b32_e32 v118, v149
	s_nop 0
	v_mov_b32_e32 v112, v190
	v_ashrrev_i32_e32 v119, 31, v118
	v_pk_mul_f32 v[126:127], v[108:109], v[112:113] op_sel_hi:[1,0]
	v_pk_mul_f32 v[114:115], v[100:101], v[112:113] op_sel_hi:[1,0]
	v_pk_mul_f32 v[122:123], v[110:111], v[112:113] op_sel_hi:[1,0]
	v_pk_mul_f32 v[110:111], v[102:103], v[112:113] op_sel_hi:[1,0]
	v_pk_mul_f32 v[108:109], v[98:99], v[112:113] op_sel_hi:[1,0]
	v_mov_b32_e32 v98, v127
	v_mov_b32_e32 v99, v115
	v_pk_mul_f32 v[106:107], v[106:107], v[112:113] op_sel_hi:[1,0]
	v_pk_mul_f32 v[104:105], v[104:105], v[112:113] op_sel_hi:[1,0]
	v_pk_mul_f32 v[112:113], v[96:97], v[112:113] op_sel_hi:[1,0]
	v_mov_b32_e32 v96, v126
	v_mov_b32_e32 v97, v114
	v_pk_mul_f32 v[98:99], v[98:99], v[98:99]
	v_mov_b32_e32 v100, v123
	v_mov_b32_e32 v101, v111
	v_pk_fma_f32 v[96:97], v[96:97], v[96:97], v[98:99]
	v_mov_b32_e32 v98, v122
	v_mov_b32_e32 v99, v110
	v_pk_mul_f32 v[100:101], v[100:101], v[100:101]
	v_mov_b32_e32 v102, v107
	v_pk_fma_f32 v[98:99], v[98:99], v[98:99], v[100:101]
	v_mov_b32_e32 v100, v105
	v_mov_b32_e32 v101, v113
	v_pk_add_f32 v[96:97], v[96:97], v[98:99]
	v_mov_b32_e32 v98, v104
	v_mov_b32_e32 v99, v112
	v_pk_mul_f32 v[100:101], v[100:101], v[100:101]
	v_mov_b32_e32 v103, v109
	v_pk_fma_f32 v[98:99], v[98:99], v[98:99], v[100:101]
	v_mov_b32_e32 v100, v106
	v_mov_b32_e32 v101, v108
	v_pk_mul_f32 v[102:103], v[102:103], v[102:103]
	s_nop 0
	v_pk_fma_f32 v[100:101], v[100:101], v[100:101], v[102:103]
	s_nop 0
	v_pk_add_f32 v[98:99], v[98:99], v[100:101]
	s_nop 0
	v_pk_add_f32 v[96:97], v[96:97], v[98:99]
	s_nop 0
	v_add_f32_e32 v96, v96, v97
	ds_bpermute_b32 v97, v135, v96
	s_waitcnt lgkmcnt(0)
	v_add_f32_e32 v96, v96, v97
	ds_bpermute_b32 v97, v155, v96
	s_waitcnt lgkmcnt(0)
	v_add_f32_e32 v96, v96, v97
	v_fmamk_f32 v96, v96, 0x3c800000, v218
	v_cmp_gt_f32_e32 vcc, s3, v96
	v_mul_f32_e32 v97, 0x4f800000, v96
	s_nop 0
	v_cndmask_b32_e32 v96, v96, v97, vcc
	v_sqrt_f32_e32 v97, v96
	s_nop 0
	v_add_u32_e32 v98, -1, v97
	v_fma_f32 v99, -v98, v97, v96
	v_cmp_ge_f32_e64 s[0:1], 0, v99
	v_add_u32_e32 v99, 1, v97
	s_nop 0
	v_cndmask_b32_e64 v98, v97, v98, s[0:1]
	v_fma_f32 v97, -v99, v97, v96
	v_cmp_lt_f32_e64 s[0:1], 0, v97
	s_nop 1
	v_cndmask_b32_e64 v97, v98, v99, s[0:1]
	v_mul_f32_e32 v98, 0x37800000, v97
	v_cndmask_b32_e32 v97, v97, v98, vcc
	v_cmp_class_f32_e32 vcc, v96, v219
	s_nop 1
	v_cndmask_b32_e32 v96, v97, v96, vcc
	v_div_scale_f32 v97, s[0:1], v96, v96, 1.0
	v_rcp_f32_e32 v98, v97
	s_nop 0
	v_fma_f32 v99, -v97, v98, 1.0
	v_fmac_f32_e32 v98, v99, v98
	v_div_scale_f32 v99, vcc, 1.0, v96, 1.0
	v_mul_f32_e32 v100, v99, v98
	v_fma_f32 v101, -v97, v100, v99
	v_fmac_f32_e32 v100, v101, v98
	v_fma_f32 v97, -v97, v100, v99
	v_div_fmas_f32 v97, v97, v98, v100
	v_div_fixup_f32 v116, v97, v96, 1.0
	v_lshlrev_b64 v[96:97], 9, v[118:119]
	v_lshl_add_u64 v[120:121], s[14:15], 0, v[96:97]
	v_lshlrev_b64 v[96:97], 10, v[118:119]
	v_lshl_add_u64 v[118:119], s[24:25], 0, v[96:97]
	global_load_dwordx4 v[96:99], v184, s[40:41] offset:16
	global_load_dwordx4 v[100:103], v184, s[40:41]
	v_pk_mul_f32 v[126:127], v[126:127], v[116:117] op_sel_hi:[1,0]
	v_pk_mul_f32 v[122:123], v[122:123], v[116:117] op_sel_hi:[1,0]
	v_pk_mul_f32 v[104:105], v[104:105], v[116:117] op_sel_hi:[1,0]
	v_pk_mul_f32 v[106:107], v[106:107], v[116:117] op_sel_hi:[1,0]
	v_lshl_add_u64 v[120:121], v[120:121], 0, v[124:125]
	v_lshl_add_u64 v[118:119], v[118:119], 0, v[184:185]
	s_waitcnt vmcnt(1)
	v_pk_mul_f32 v[98:99], v[98:99], v[106:107]
	s_waitcnt vmcnt(0)
	v_pk_mul_f32 v[102:103], v[102:103], v[122:123]
	v_pk_mul_f32 v[100:101], v[100:101], v[126:127]
	v_pk_mul_f32 v[96:97], v[96:97], v[104:105]
	v_cvt_pk_bf16_f32 v104, v100, v101
	v_cvt_pk_bf16_f32 v105, v102, v103
	s_nop 0
	v_cvt_pk_bf16_f32 v106, v96, v97
	v_cvt_pk_bf16_f32 v107, v98, v99
	global_store_dwordx4 v[120:121], v[104:107], off
	global_store_dwordx4 v[118:119], v[100:103], off nt
	global_store_dwordx4 v[118:119], v[96:99], off offset:16 nt
	global_load_dwordx4 v[96:99], v169, s[40:41] offset:16
	s_nop 0
	global_load_dwordx4 v[100:103], v169, s[40:41]
	v_pk_mul_f32 v[104:105], v[114:115], v[116:117] op_sel_hi:[1,0]
	v_pk_mul_f32 v[106:107], v[110:111], v[116:117] op_sel_hi:[1,0]
	s_waitcnt vmcnt(0)
; __device__ __forceinline__ float quad_sum(float s) { s += __shfl_xor(s, 16); s += __shfl_xor(s, 32); return s; }
; __device__ __forceinline__ float sq4(const f32x4 a) { return (a[0] * a[0] + a[1] * a[1]) + (a[2] * a[2] + a[3] * a[3]); }
; __device__ __forceinline__ u32x4 pack8(const f32x4 a, const f32x4 b) { u32x4 w; w.x = cvt_pk_bf16(a[0], a[1]); w.y = cvt_pk_bf16(a[2], a[3]); w.z = cvt_pk_bf16(b[0], b[1]); w.w = cvt_pk_bf16(b[2], b[3]); return w; }
;     __device__ __forceinline__ void operator()(const f32x4 (&acc)[2][2][4][2], const Unit& u, int wr, int wc, int fr, int fq) const {
;     ...
;                     int mrow = ai * HALF + wr * 64 + m * 16 + fr;
;                     asm volatile("" : "+v"(mrow));
;                     const float rs = MRS[b * 256 + mrow];
;                     f32x4 v[2][2];
; #pragma unroll
;                     for (int bj = 0; bj < 2; ++bj)
; #pragma unroll
;                         for (int n = 0; n < 2; ++n) v[bj][n] = acc[ai][bj][m][n] * rs;
;                     float ss = (sq4(v[0][0]) + sq4(v[0][1])) + (sq4(v[1][0]) + sq4(v[1][1]));
;                     ss = quad_sum(ss);
;                     const float hr = 1.0f / sqrtf(ss * (1.0f / 64.0f) + E_EPS);
; #pragma unroll
;                     for (int bj = 0; bj < 2; ++bj) {
;                         const int c0 = bj * 32 + 8 * fq;
;                         const f32x4 g0 = *(const f32x4*)(g + c0), g1 = *(const f32x4*)(g + c0 + 4);
;                         const f32x4 o0 = v[bj][0] * hr * g0, o1 = v[bj][1] * hr * g1;
;                         *(u32x4*)(MK + ((size_t)(l * 40 + b) * 256 + mrow) * 256 + wc * 64 + c0) = pack8(o0, o1);
;                         float* d = o_mk + ((size_t)(l * 8 + b) * 256 + mrow) * 256 + wc * 64 + c0; __builtin_nontemporal_store(o0, (f32x4*)d); __builtin_nontemporal_store(o1, (f32x4*)(d + 4));
;                     }
	v_pk_mul_f32 v[100:101], v[100:101], v[104:105]
	v_pk_mul_f32 v[102:103], v[102:103], v[106:107]
	v_pk_mul_f32 v[104:105], v[112:113], v[116:117] op_sel_hi:[1,0]
	v_pk_mul_f32 v[106:107], v[108:109], v[116:117] op_sel_hi:[1,0]
	v_pk_mul_f32 v[96:97], v[96:97], v[104:105]
	v_pk_mul_f32 v[98:99], v[98:99], v[106:107]
	v_cvt_pk_bf16_f32 v104, v100, v101
	v_cvt_pk_bf16_f32 v105, v102, v103
	v_cvt_pk_bf16_f32 v106, v96, v97
	s_nop 0
	v_cvt_pk_bf16_f32 v107, v98, v99
	global_store_dwordx4 v[120:121], v[104:107], off offset:64
	global_store_dwordx4 v[118:119], v[100:103], off offset:128 nt
	global_store_dwordx4 v[118:119], v[96:99], off offset:144 nt
	s_nop 0
	v_mov_b32_e32 v102, v162
	s_nop 0
	v_mov_b32_e32 v96, v191
	v_ashrrev_i32_e32 v103, 31, v102
	v_pk_mul_f32 v[108:109], v[92:93], v[96:97] op_sel_hi:[1,0]
	v_pk_mul_f32 v[98:99], v[84:85], v[96:97] op_sel_hi:[1,0]
	v_pk_mul_f32 v[106:107], v[94:95], v[96:97] op_sel_hi:[1,0]
	v_pk_mul_f32 v[94:95], v[86:87], v[96:97] op_sel_hi:[1,0]
	v_pk_mul_f32 v[92:93], v[82:83], v[96:97] op_sel_hi:[1,0]
	v_mov_b32_e32 v82, v109
	v_mov_b32_e32 v83, v99
	v_pk_mul_f32 v[90:91], v[90:91], v[96:97] op_sel_hi:[1,0]
	v_pk_mul_f32 v[88:89], v[88:89], v[96:97] op_sel_hi:[1,0]
	v_pk_mul_f32 v[96:97], v[80:81], v[96:97] op_sel_hi:[1,0]
	v_mov_b32_e32 v80, v108
	v_mov_b32_e32 v81, v98
	v_pk_mul_f32 v[82:83], v[82:83], v[82:83]
	v_mov_b32_e32 v84, v107
	v_mov_b32_e32 v85, v95
	v_pk_fma_f32 v[80:81], v[80:81], v[80:81], v[82:83]
	v_mov_b32_e32 v82, v106
	v_mov_b32_e32 v83, v94
	v_pk_mul_f32 v[84:85], v[84:85], v[84:85]
	v_mov_b32_e32 v86, v91
	v_pk_fma_f32 v[82:83], v[82:83], v[82:83], v[84:85]
	v_mov_b32_e32 v84, v89
	v_mov_b32_e32 v85, v97
	v_pk_add_f32 v[80:81], v[80:81], v[82:83]
	v_mov_b32_e32 v82, v88
	v_mov_b32_e32 v83, v96
	v_pk_mul_f32 v[84:85], v[84:85], v[84:85]
	v_mov_b32_e32 v87, v93
	v_pk_fma_f32 v[82:83], v[82:83], v[82:83], v[84:85]
	v_mov_b32_e32 v84, v90
	v_mov_b32_e32 v85, v92
	v_pk_mul_f32 v[86:87], v[86:87], v[86:87]
	s_nop 0
	v_pk_fma_f32 v[84:85], v[84:85], v[84:85], v[86:87]
	s_nop 0
	v_pk_add_f32 v[82:83], v[82:83], v[84:85]
	s_nop 0
	v_pk_add_f32 v[80:81], v[80:81], v[82:83]
	s_nop 0
	v_add_f32_e32 v80, v80, v81
	ds_bpermute_b32 v81, v135, v80
	s_waitcnt lgkmcnt(0)
	v_add_f32_e32 v80, v80, v81
	ds_bpermute_b32 v81, v155, v80
	s_waitcnt lgkmcnt(0)
	v_add_f32_e32 v80, v80, v81
	v_fmamk_f32 v80, v80, 0x3c800000, v218
	v_cmp_gt_f32_e32 vcc, s3, v80
	v_mul_f32_e32 v81, 0x4f800000, v80
	s_nop 0
	v_cndmask_b32_e32 v80, v80, v81, vcc
	v_sqrt_f32_e32 v81, v80
	s_nop 0
	v_add_u32_e32 v82, -1, v81
	v_fma_f32 v83, -v82, v81, v80
	v_cmp_ge_f32_e64 s[0:1], 0, v83
	v_add_u32_e32 v83, 1, v81
	s_nop 0
	v_cndmask_b32_e64 v82, v81, v82, s[0:1]
	v_fma_f32 v81, -v83, v81, v80
	v_cmp_lt_f32_e64 s[0:1], 0, v81
	s_nop 1
	v_cndmask_b32_e64 v81, v82, v83, s[0:1]
	v_mul_f32_e32 v82, 0x37800000, v81
	v_cndmask_b32_e32 v81, v81, v82, vcc
	v_cmp_class_f32_e32 vcc, v80, v219
	s_nop 1
	v_cndmask_b32_e32 v80, v81, v80, vcc
	v_div_scale_f32 v81, s[0:1], v80, v80, 1.0
	v_rcp_f32_e32 v82, v81
	s_nop 0
	v_fma_f32 v83, -v81, v82, 1.0
	v_fmac_f32_e32 v82, v83, v82
	v_div_scale_f32 v83, vcc, 1.0, v80, 1.0
	v_mul_f32_e32 v84, v83, v82
	v_fma_f32 v85, -v81, v84, v83
	v_fmac_f32_e32 v84, v85, v82
	v_fma_f32 v81, -v81, v84, v83
	v_div_fmas_f32 v81, v81, v82, v84
	v_div_fixup_f32 v100, v81, v80, 1.0
	v_lshlrev_b64 v[80:81], 9, v[102:103]
	v_lshl_add_u64 v[104:105], s[14:15], 0, v[80:81]
	v_lshlrev_b64 v[80:81], 10, v[102:103]
	v_lshl_add_u64 v[102:103], s[24:25], 0, v[80:81]
	global_load_dwordx4 v[80:83], v184, s[40:41] offset:16
	global_load_dwordx4 v[84:87], v184, s[40:41]
	v_pk_mul_f32 v[108:109], v[108:109], v[100:101] op_sel_hi:[1,0]
	v_pk_mul_f32 v[106:107], v[106:107], v[100:101] op_sel_hi:[1,0]
	v_pk_mul_f32 v[88:89], v[88:89], v[100:101] op_sel_hi:[1,0]
	v_pk_mul_f32 v[90:91], v[90:91], v[100:101] op_sel_hi:[1,0]
	v_lshl_add_u64 v[104:105], v[104:105], 0, v[124:125]
	v_lshl_add_u64 v[102:103], v[102:103], 0, v[184:185]
	s_waitcnt vmcnt(1)
	v_pk_mul_f32 v[82:83], v[82:83], v[90:91]
	s_waitcnt vmcnt(0)
	v_pk_mul_f32 v[86:87], v[86:87], v[106:107]
	v_pk_mul_f32 v[84:85], v[84:85], v[108:109]
	v_pk_mul_f32 v[80:81], v[80:81], v[88:89]
	v_cvt_pk_bf16_f32 v88, v84, v85
	v_cvt_pk_bf16_f32 v89, v86, v87
	s_nop 0
	v_cvt_pk_bf16_f32 v90, v80, v81
	v_cvt_pk_bf16_f32 v91, v82, v83
	global_store_dwordx4 v[104:105], v[88:91], off
	global_store_dwordx4 v[102:103], v[84:87], off nt
	global_store_dwordx4 v[102:103], v[80:83], off offset:16 nt
	global_load_dwordx4 v[80:83], v169, s[40:41] offset:16
	s_nop 0
	global_load_dwordx4 v[84:87], v169, s[40:41]
	v_pk_mul_f32 v[88:89], v[98:99], v[100:101] op_sel_hi:[1,0]
	v_pk_mul_f32 v[90:91], v[94:95], v[100:101] op_sel_hi:[1,0]
	s_waitcnt vmcnt(0)
; __device__ __forceinline__ float quad_sum(float s) { s += __shfl_xor(s, 16); s += __shfl_xor(s, 32); return s; }
; __device__ __forceinline__ float sq4(const f32x4 a) { return (a[0] * a[0] + a[1] * a[1]) + (a[2] * a[2] + a[3] * a[3]); }
; __device__ __forceinline__ u32x4 pack8(const f32x4 a, const f32x4 b) { u32x4 w; w.x = cvt_pk_bf16(a[0], a[1]); w.y = cvt_pk_bf16(a[2], a[3]); w.z = cvt_pk_bf16(b[0], b[1]); w.w = cvt_pk_bf16(b[2], b[3]); return w; }
;     __device__ __forceinline__ void operator()(const f32x4 (&acc)[2][2][4][2], const Unit& u, int wr, int wc, int fr, int fq) const {
;     ...
;                     int mrow = ai * HALF + wr * 64 + m * 16 + fr;
;                     asm volatile("" : "+v"(mrow));
;                     const float rs = MRS[b * 256 + mrow];
;                     f32x4 v[2][2];
; #pragma unroll
;                     for (int bj = 0; bj < 2; ++bj)
; #pragma unroll
;                         for (int n = 0; n < 2; ++n) v[bj][n] = acc[ai][bj][m][n] * rs;
;                     float ss = (sq4(v[0][0]) + sq4(v[0][1])) + (sq4(v[1][0]) + sq4(v[1][1]));
;                     ss = quad_sum(ss);
;                     const float hr = 1.0f / sqrtf(ss * (1.0f / 64.0f) + E_EPS);
; #pragma unroll
;                     for (int bj = 0; bj < 2; ++bj) {
;                         const int c0 = bj * 32 + 8 * fq;
;                         const f32x4 g0 = *(const f32x4*)(g + c0), g1 = *(const f32x4*)(g + c0 + 4);
;                         const f32x4 o0 = v[bj][0] * hr * g0, o1 = v[bj][1] * hr * g1;
;                         *(u32x4*)(MK + ((size_t)(l * 40 + b) * 256 + mrow) * 256 + wc * 64 + c0) = pack8(o0, o1);
;                         float* d = o_mk + ((size_t)(l * 8 + b) * 256 + mrow) * 256 + wc * 64 + c0; __builtin_nontemporal_store(o0, (f32x4*)d); __builtin_nontemporal_store(o1, (f32x4*)(d + 4));
;                     }
	v_pk_mul_f32 v[84:85], v[84:85], v[88:89]
	v_pk_mul_f32 v[86:87], v[86:87], v[90:91]
	v_pk_mul_f32 v[88:89], v[96:97], v[100:101] op_sel_hi:[1,0]
	v_pk_mul_f32 v[90:91], v[92:93], v[100:101] op_sel_hi:[1,0]
	v_pk_mul_f32 v[80:81], v[80:81], v[88:89]
	v_pk_mul_f32 v[82:83], v[82:83], v[90:91]
	v_cvt_pk_bf16_f32 v88, v84, v85
	v_cvt_pk_bf16_f32 v89, v86, v87
	v_cvt_pk_bf16_f32 v90, v80, v81
	s_nop 0
	v_cvt_pk_bf16_f32 v91, v82, v83
	global_store_dwordx4 v[104:105], v[88:91], off offset:64
	global_store_dwordx4 v[102:103], v[84:87], off offset:128 nt
	global_store_dwordx4 v[102:103], v[80:83], off offset:144 nt
	s_nop 0
	v_mov_b32_e32 v86, v163
	s_nop 0
	v_mov_b32_e32 v80, v217
	v_ashrrev_i32_e32 v87, 31, v86
	v_pk_mul_f32 v[92:93], v[76:77], v[80:81] op_sel_hi:[1,0]
	v_pk_mul_f32 v[82:83], v[68:69], v[80:81] op_sel_hi:[1,0]
	v_pk_mul_f32 v[90:91], v[78:79], v[80:81] op_sel_hi:[1,0]
	v_pk_mul_f32 v[78:79], v[70:71], v[80:81] op_sel_hi:[1,0]
	v_pk_mul_f32 v[76:77], v[66:67], v[80:81] op_sel_hi:[1,0]
	v_mov_b32_e32 v66, v93
	v_mov_b32_e32 v67, v83
	v_pk_mul_f32 v[74:75], v[74:75], v[80:81] op_sel_hi:[1,0]
	v_pk_mul_f32 v[72:73], v[72:73], v[80:81] op_sel_hi:[1,0]
	v_pk_mul_f32 v[80:81], v[64:65], v[80:81] op_sel_hi:[1,0]
	v_mov_b32_e32 v64, v92
	v_mov_b32_e32 v65, v82
	v_pk_mul_f32 v[66:67], v[66:67], v[66:67]
	v_mov_b32_e32 v68, v91
	v_mov_b32_e32 v69, v79
	v_pk_fma_f32 v[64:65], v[64:65], v[64:65], v[66:67]
	v_mov_b32_e32 v66, v90
	v_mov_b32_e32 v67, v78
	v_pk_mul_f32 v[68:69], v[68:69], v[68:69]
	v_mov_b32_e32 v70, v75
	v_pk_fma_f32 v[66:67], v[66:67], v[66:67], v[68:69]
	v_mov_b32_e32 v68, v73
	v_mov_b32_e32 v69, v81
	v_pk_add_f32 v[64:65], v[64:65], v[66:67]
	v_mov_b32_e32 v66, v72
	v_mov_b32_e32 v67, v80
	v_pk_mul_f32 v[68:69], v[68:69], v[68:69]
	v_mov_b32_e32 v71, v77
	v_pk_fma_f32 v[66:67], v[66:67], v[66:67], v[68:69]
	v_mov_b32_e32 v68, v74
	v_mov_b32_e32 v69, v76
	v_pk_mul_f32 v[70:71], v[70:71], v[70:71]
	s_nop 0
	v_pk_fma_f32 v[68:69], v[68:69], v[68:69], v[70:71]
	s_nop 0
	v_pk_add_f32 v[66:67], v[66:67], v[68:69]
	s_nop 0
	v_pk_add_f32 v[64:65], v[64:65], v[66:67]
	s_nop 0
	v_add_f32_e32 v64, v64, v65
	ds_bpermute_b32 v65, v135, v64
	s_waitcnt lgkmcnt(0)
	v_add_f32_e32 v64, v64, v65
	ds_bpermute_b32 v65, v155, v64
	s_waitcnt lgkmcnt(0)
	v_add_f32_e32 v64, v64, v65
	v_fmamk_f32 v64, v64, 0x3c800000, v218
	v_cmp_gt_f32_e32 vcc, s3, v64
	v_mul_f32_e32 v65, 0x4f800000, v64
	s_nop 0
	v_cndmask_b32_e32 v64, v64, v65, vcc
	v_sqrt_f32_e32 v65, v64
	s_nop 0
	v_add_u32_e32 v66, -1, v65
	v_fma_f32 v67, -v66, v65, v64
	v_cmp_ge_f32_e64 s[0:1], 0, v67
	v_add_u32_e32 v67, 1, v65
	s_nop 0
	v_cndmask_b32_e64 v66, v65, v66, s[0:1]
	v_fma_f32 v65, -v67, v65, v64
	v_cmp_lt_f32_e64 s[0:1], 0, v65
	s_nop 1
	v_cndmask_b32_e64 v65, v66, v67, s[0:1]
	v_mul_f32_e32 v66, 0x37800000, v65
	v_cndmask_b32_e32 v65, v65, v66, vcc
	v_cmp_class_f32_e32 vcc, v64, v219
	s_nop 1
	v_cndmask_b32_e32 v64, v65, v64, vcc
	v_div_scale_f32 v65, s[0:1], v64, v64, 1.0
	v_rcp_f32_e32 v66, v65
	s_nop 0
	v_fma_f32 v67, -v65, v66, 1.0
	v_fmac_f32_e32 v66, v67, v66
	v_div_scale_f32 v67, vcc, 1.0, v64, 1.0
	v_mul_f32_e32 v68, v67, v66
	v_fma_f32 v69, -v65, v68, v67
	v_fmac_f32_e32 v68, v69, v66
	v_fma_f32 v65, -v65, v68, v67
	v_div_fmas_f32 v65, v65, v66, v68
	v_div_fixup_f32 v84, v65, v64, 1.0
	v_lshlrev_b64 v[64:65], 9, v[86:87]
	v_lshl_add_u64 v[88:89], s[14:15], 0, v[64:65]
	v_lshlrev_b64 v[64:65], 10, v[86:87]
	v_lshl_add_u64 v[86:87], s[24:25], 0, v[64:65]
	global_load_dwordx4 v[64:67], v184, s[40:41] offset:16
	global_load_dwordx4 v[68:71], v184, s[40:41]
	v_pk_mul_f32 v[92:93], v[92:93], v[84:85] op_sel_hi:[1,0]
	v_pk_mul_f32 v[90:91], v[90:91], v[84:85] op_sel_hi:[1,0]
	v_pk_mul_f32 v[72:73], v[72:73], v[84:85] op_sel_hi:[1,0]
	v_pk_mul_f32 v[74:75], v[74:75], v[84:85] op_sel_hi:[1,0]
	v_lshl_add_u64 v[88:89], v[88:89], 0, v[124:125]
	v_lshl_add_u64 v[86:87], v[86:87], 0, v[184:185]
	s_waitcnt vmcnt(1)
	v_pk_mul_f32 v[66:67], v[66:67], v[74:75]
	s_waitcnt vmcnt(0)
	v_pk_mul_f32 v[70:71], v[70:71], v[90:91]
	v_pk_mul_f32 v[68:69], v[68:69], v[92:93]
	v_pk_mul_f32 v[64:65], v[64:65], v[72:73]
	v_cvt_pk_bf16_f32 v72, v68, v69
	v_cvt_pk_bf16_f32 v73, v70, v71
	s_nop 0
	v_cvt_pk_bf16_f32 v74, v64, v65
	v_cvt_pk_bf16_f32 v75, v66, v67
	global_store_dwordx4 v[88:89], v[72:75], off
	global_store_dwordx4 v[86:87], v[68:71], off nt
	global_store_dwordx4 v[86:87], v[64:67], off offset:16 nt
	global_load_dwordx4 v[64:67], v169, s[40:41] offset:16
	s_nop 0
	global_load_dwordx4 v[68:71], v169, s[40:41]
	v_pk_mul_f32 v[72:73], v[82:83], v[84:85] op_sel_hi:[1,0]
	v_pk_mul_f32 v[74:75], v[78:79], v[84:85] op_sel_hi:[1,0]
	s_waitcnt vmcnt(0)
; __device__ __forceinline__ float quad_sum(float s) { s += __shfl_xor(s, 16); s += __shfl_xor(s, 32); return s; }
; __device__ __forceinline__ float sq4(const f32x4 a) { return (a[0] * a[0] + a[1] * a[1]) + (a[2] * a[2] + a[3] * a[3]); }
; __device__ __forceinline__ u32x4 pack8(const f32x4 a, const f32x4 b) { u32x4 w; w.x = cvt_pk_bf16(a[0], a[1]); w.y = cvt_pk_bf16(a[2], a[3]); w.z = cvt_pk_bf16(b[0], b[1]); w.w = cvt_pk_bf16(b[2], b[3]); return w; }
;     __device__ __forceinline__ void operator()(const f32x4 (&acc)[2][2][4][2], const Unit& u, int wr, int wc, int fr, int fq) const {
;     ...
;                     int mrow = ai * HALF + wr * 64 + m * 16 + fr;
;                     asm volatile("" : "+v"(mrow));
;                     const float rs = MRS[b * 256 + mrow];
;                     f32x4 v[2][2];
; #pragma unroll
;                     for (int bj = 0; bj < 2; ++bj)
; #pragma unroll
;                         for (int n = 0; n < 2; ++n) v[bj][n] = acc[ai][bj][m][n] * rs;
;                     float ss = (sq4(v[0][0]) + sq4(v[0][1])) + (sq4(v[1][0]) + sq4(v[1][1]));
;                     ss = quad_sum(ss);
;                     const float hr = 1.0f / sqrtf(ss * (1.0f / 64.0f) + E_EPS);
; #pragma unroll
;                     for (int bj = 0; bj < 2; ++bj) {
;                         const int c0 = bj * 32 + 8 * fq;
;                         const f32x4 g0 = *(const f32x4*)(g + c0), g1 = *(const f32x4*)(g + c0 + 4);
;                         const f32x4 o0 = v[bj][0] * hr * g0, o1 = v[bj][1] * hr * g1;
;                         *(u32x4*)(MK + ((size_t)(l * 40 + b) * 256 + mrow) * 256 + wc * 64 + c0) = pack8(o0, o1);
;                         float* d = o_mk + ((size_t)(l * 8 + b) * 256 + mrow) * 256 + wc * 64 + c0; __builtin_nontemporal_store(o0, (f32x4*)d); __builtin_nontemporal_store(o1, (f32x4*)(d + 4));
;                     }
	v_pk_mul_f32 v[68:69], v[68:69], v[72:73]
	v_pk_mul_f32 v[70:71], v[70:71], v[74:75]
	v_pk_mul_f32 v[72:73], v[80:81], v[84:85] op_sel_hi:[1,0]
	v_pk_mul_f32 v[74:75], v[76:77], v[84:85] op_sel_hi:[1,0]
	v_pk_mul_f32 v[64:65], v[64:65], v[72:73]
	v_pk_mul_f32 v[66:67], v[66:67], v[74:75]
	v_cvt_pk_bf16_f32 v72, v68, v69
	v_cvt_pk_bf16_f32 v73, v70, v71
	v_cvt_pk_bf16_f32 v74, v64, v65
	s_nop 0
	v_cvt_pk_bf16_f32 v75, v66, v67
	global_store_dwordx4 v[88:89], v[72:75], off offset:64
	global_store_dwordx4 v[86:87], v[68:71], off offset:128 nt
	global_store_dwordx4 v[86:87], v[64:67], off offset:144 nt
	s_nop 0
	v_mov_b32_e32 v70, v164
	s_nop 0
	v_mov_b32_e32 v64, v220
	v_ashrrev_i32_e32 v71, 31, v70
	v_pk_mul_f32 v[76:77], v[60:61], v[64:65] op_sel_hi:[1,0]
	v_pk_mul_f32 v[66:67], v[52:53], v[64:65] op_sel_hi:[1,0]
	v_pk_mul_f32 v[74:75], v[62:63], v[64:65] op_sel_hi:[1,0]
	v_pk_mul_f32 v[62:63], v[54:55], v[64:65] op_sel_hi:[1,0]
	v_pk_mul_f32 v[60:61], v[50:51], v[64:65] op_sel_hi:[1,0]
	v_mov_b32_e32 v50, v77
	v_mov_b32_e32 v51, v67
	v_pk_mul_f32 v[58:59], v[58:59], v[64:65] op_sel_hi:[1,0]
	v_pk_mul_f32 v[56:57], v[56:57], v[64:65] op_sel_hi:[1,0]
	v_pk_mul_f32 v[64:65], v[48:49], v[64:65] op_sel_hi:[1,0]
	v_mov_b32_e32 v48, v76
	v_mov_b32_e32 v49, v66
	v_pk_mul_f32 v[50:51], v[50:51], v[50:51]
	v_mov_b32_e32 v52, v75
	v_mov_b32_e32 v53, v63
	v_pk_fma_f32 v[48:49], v[48:49], v[48:49], v[50:51]
	v_mov_b32_e32 v50, v74
	v_mov_b32_e32 v51, v62
	v_pk_mul_f32 v[52:53], v[52:53], v[52:53]
	v_mov_b32_e32 v54, v59
	v_pk_fma_f32 v[50:51], v[50:51], v[50:51], v[52:53]
	v_mov_b32_e32 v52, v57
	v_mov_b32_e32 v53, v65
	v_pk_add_f32 v[48:49], v[48:49], v[50:51]
	v_mov_b32_e32 v50, v56
	v_mov_b32_e32 v51, v64
	v_pk_mul_f32 v[52:53], v[52:53], v[52:53]
	v_mov_b32_e32 v55, v61
	v_pk_fma_f32 v[50:51], v[50:51], v[50:51], v[52:53]
	v_mov_b32_e32 v52, v58
	v_mov_b32_e32 v53, v60
	v_pk_mul_f32 v[54:55], v[54:55], v[54:55]
	s_nop 0
	v_pk_fma_f32 v[52:53], v[52:53], v[52:53], v[54:55]
	s_nop 0
	v_pk_add_f32 v[50:51], v[50:51], v[52:53]
	s_nop 0
	v_pk_add_f32 v[48:49], v[48:49], v[50:51]
	s_nop 0
	v_add_f32_e32 v48, v48, v49
	ds_bpermute_b32 v49, v135, v48
	s_waitcnt lgkmcnt(0)
	v_add_f32_e32 v48, v48, v49
	ds_bpermute_b32 v49, v155, v48
	s_waitcnt lgkmcnt(0)
	v_add_f32_e32 v48, v48, v49
	v_fmamk_f32 v48, v48, 0x3c800000, v218
	v_cmp_gt_f32_e32 vcc, s3, v48
	v_mul_f32_e32 v49, 0x4f800000, v48
	s_nop 0
	v_cndmask_b32_e32 v48, v48, v49, vcc
	v_sqrt_f32_e32 v49, v48
	s_nop 0
	v_add_u32_e32 v50, -1, v49
	v_fma_f32 v51, -v50, v49, v48
	v_cmp_ge_f32_e64 s[0:1], 0, v51
	v_add_u32_e32 v51, 1, v49
	s_nop 0
	v_cndmask_b32_e64 v50, v49, v50, s[0:1]
	v_fma_f32 v49, -v51, v49, v48
	v_cmp_lt_f32_e64 s[0:1], 0, v49
	s_nop 1
	v_cndmask_b32_e64 v49, v50, v51, s[0:1]
	v_mul_f32_e32 v50, 0x37800000, v49
	v_cndmask_b32_e32 v49, v49, v50, vcc
	v_cmp_class_f32_e32 vcc, v48, v219
	s_nop 1
	v_cndmask_b32_e32 v48, v49, v48, vcc
	v_div_scale_f32 v49, s[0:1], v48, v48, 1.0
	v_rcp_f32_e32 v50, v49
	s_nop 0
	v_fma_f32 v51, -v49, v50, 1.0
	v_fmac_f32_e32 v50, v51, v50
	v_div_scale_f32 v51, vcc, 1.0, v48, 1.0
	v_mul_f32_e32 v52, v51, v50
	v_fma_f32 v53, -v49, v52, v51
	v_fmac_f32_e32 v52, v53, v50
	v_fma_f32 v49, -v49, v52, v51
	v_div_fmas_f32 v49, v49, v50, v52
	v_div_fixup_f32 v68, v49, v48, 1.0
	v_lshlrev_b64 v[48:49], 9, v[70:71]
	v_lshl_add_u64 v[72:73], s[14:15], 0, v[48:49]
	v_lshlrev_b64 v[48:49], 10, v[70:71]
	v_lshl_add_u64 v[70:71], s[24:25], 0, v[48:49]
	global_load_dwordx4 v[48:51], v184, s[40:41] offset:16
	global_load_dwordx4 v[52:55], v184, s[40:41]
	v_pk_mul_f32 v[76:77], v[76:77], v[68:69] op_sel_hi:[1,0]
	v_pk_mul_f32 v[74:75], v[74:75], v[68:69] op_sel_hi:[1,0]
	v_pk_mul_f32 v[56:57], v[56:57], v[68:69] op_sel_hi:[1,0]
	v_pk_mul_f32 v[58:59], v[58:59], v[68:69] op_sel_hi:[1,0]
	v_lshl_add_u64 v[72:73], v[72:73], 0, v[124:125]
	v_lshl_add_u64 v[70:71], v[70:71], 0, v[184:185]
	s_waitcnt vmcnt(1)
	v_pk_mul_f32 v[50:51], v[50:51], v[58:59]
	s_waitcnt vmcnt(0)
	v_pk_mul_f32 v[54:55], v[54:55], v[74:75]
	v_pk_mul_f32 v[52:53], v[52:53], v[76:77]
	v_pk_mul_f32 v[48:49], v[48:49], v[56:57]
	v_cvt_pk_bf16_f32 v56, v52, v53
	v_cvt_pk_bf16_f32 v57, v54, v55
	s_nop 0
	v_cvt_pk_bf16_f32 v58, v48, v49
	v_cvt_pk_bf16_f32 v59, v50, v51
	global_store_dwordx4 v[72:73], v[56:59], off
	global_store_dwordx4 v[70:71], v[52:55], off nt
	global_store_dwordx4 v[70:71], v[48:51], off offset:16 nt
	global_load_dwordx4 v[48:51], v169, s[40:41] offset:16
	s_nop 0
	global_load_dwordx4 v[52:55], v169, s[40:41]
	v_pk_mul_f32 v[56:57], v[66:67], v[68:69] op_sel_hi:[1,0]
	v_pk_mul_f32 v[58:59], v[62:63], v[68:69] op_sel_hi:[1,0]
	s_waitcnt vmcnt(0)
; __device__ __forceinline__ float quad_sum(float s) { s += __shfl_xor(s, 16); s += __shfl_xor(s, 32); return s; }
; __device__ __forceinline__ float sq4(const f32x4 a) { return (a[0] * a[0] + a[1] * a[1]) + (a[2] * a[2] + a[3] * a[3]); }
; __device__ __forceinline__ u32x4 pack8(const f32x4 a, const f32x4 b) { u32x4 w; w.x = cvt_pk_bf16(a[0], a[1]); w.y = cvt_pk_bf16(a[2], a[3]); w.z = cvt_pk_bf16(b[0], b[1]); w.w = cvt_pk_bf16(b[2], b[3]); return w; }
;     __device__ __forceinline__ void operator()(const f32x4 (&acc)[2][2][4][2], const Unit& u, int wr, int wc, int fr, int fq) const {
;     ...
;                     int mrow = ai * HALF + wr * 64 + m * 16 + fr;
;                     asm volatile("" : "+v"(mrow));
;                     const float rs = MRS[b * 256 + mrow];
;                     f32x4 v[2][2];
; #pragma unroll
;                     for (int bj = 0; bj < 2; ++bj)
; #pragma unroll
;                         for (int n = 0; n < 2; ++n) v[bj][n] = acc[ai][bj][m][n] * rs;
;                     float ss = (sq4(v[0][0]) + sq4(v[0][1])) + (sq4(v[1][0]) + sq4(v[1][1]));
;                     ss = quad_sum(ss);
;                     const float hr = 1.0f / sqrtf(ss * (1.0f / 64.0f) + E_EPS);
; #pragma unroll
;                     for (int bj = 0; bj < 2; ++bj) {
;                         const int c0 = bj * 32 + 8 * fq;
;                         const f32x4 g0 = *(const f32x4*)(g + c0), g1 = *(const f32x4*)(g + c0 + 4);
;                         const f32x4 o0 = v[bj][0] * hr * g0, o1 = v[bj][1] * hr * g1;
;                         *(u32x4*)(MK + ((size_t)(l * 40 + b) * 256 + mrow) * 256 + wc * 64 + c0) = pack8(o0, o1);
;                         float* d = o_mk + ((size_t)(l * 8 + b) * 256 + mrow) * 256 + wc * 64 + c0; __builtin_nontemporal_store(o0, (f32x4*)d); __builtin_nontemporal_store(o1, (f32x4*)(d + 4));
;                     }
	v_pk_mul_f32 v[52:53], v[52:53], v[56:57]
	v_pk_mul_f32 v[54:55], v[54:55], v[58:59]
	v_pk_mul_f32 v[56:57], v[64:65], v[68:69] op_sel_hi:[1,0]
	v_pk_mul_f32 v[58:59], v[60:61], v[68:69] op_sel_hi:[1,0]
	v_pk_mul_f32 v[48:49], v[48:49], v[56:57]
	v_pk_mul_f32 v[50:51], v[50:51], v[58:59]
	v_cvt_pk_bf16_f32 v56, v52, v53
	v_cvt_pk_bf16_f32 v57, v54, v55
	v_cvt_pk_bf16_f32 v58, v48, v49
	s_nop 0
	v_cvt_pk_bf16_f32 v59, v50, v51
	global_store_dwordx4 v[72:73], v[56:59], off offset:64
	global_store_dwordx4 v[70:71], v[52:55], off offset:128 nt
	global_store_dwordx4 v[70:71], v[48:51], off offset:144 nt
	s_nop 0
	v_mov_b32_e32 v54, v165
	s_nop 0
	v_mov_b32_e32 v48, v223
	v_ashrrev_i32_e32 v55, 31, v54
	v_pk_mul_f32 v[60:61], v[44:45], v[48:49] op_sel_hi:[1,0]
	v_pk_mul_f32 v[50:51], v[36:37], v[48:49] op_sel_hi:[1,0]
	v_pk_mul_f32 v[58:59], v[46:47], v[48:49] op_sel_hi:[1,0]
	v_pk_mul_f32 v[46:47], v[38:39], v[48:49] op_sel_hi:[1,0]
	v_pk_mul_f32 v[44:45], v[34:35], v[48:49] op_sel_hi:[1,0]
	v_mov_b32_e32 v34, v61
	v_mov_b32_e32 v35, v51
	v_pk_mul_f32 v[42:43], v[42:43], v[48:49] op_sel_hi:[1,0]
	v_pk_mul_f32 v[40:41], v[40:41], v[48:49] op_sel_hi:[1,0]
	v_pk_mul_f32 v[48:49], v[32:33], v[48:49] op_sel_hi:[1,0]
	v_mov_b32_e32 v32, v60
	v_mov_b32_e32 v33, v50
	v_pk_mul_f32 v[34:35], v[34:35], v[34:35]
	v_mov_b32_e32 v36, v59
	v_mov_b32_e32 v37, v47
	v_pk_fma_f32 v[32:33], v[32:33], v[32:33], v[34:35]
	v_mov_b32_e32 v34, v58
	v_mov_b32_e32 v35, v46
	v_pk_mul_f32 v[36:37], v[36:37], v[36:37]
	v_mov_b32_e32 v38, v43
	v_pk_fma_f32 v[34:35], v[34:35], v[34:35], v[36:37]
	v_mov_b32_e32 v36, v41
	v_mov_b32_e32 v37, v49
	v_pk_add_f32 v[32:33], v[32:33], v[34:35]
	v_mov_b32_e32 v34, v40
	v_mov_b32_e32 v35, v48
	v_pk_mul_f32 v[36:37], v[36:37], v[36:37]
	v_mov_b32_e32 v39, v45
	v_pk_fma_f32 v[34:35], v[34:35], v[34:35], v[36:37]
	v_mov_b32_e32 v36, v42
	v_mov_b32_e32 v37, v44
	v_pk_mul_f32 v[38:39], v[38:39], v[38:39]
	s_nop 0
	v_pk_fma_f32 v[36:37], v[36:37], v[36:37], v[38:39]
	s_nop 0
	v_pk_add_f32 v[34:35], v[34:35], v[36:37]
	s_nop 0
	v_pk_add_f32 v[32:33], v[32:33], v[34:35]
	s_nop 0
	v_add_f32_e32 v32, v32, v33
	ds_bpermute_b32 v33, v135, v32
	s_waitcnt lgkmcnt(0)
	v_add_f32_e32 v32, v32, v33
	ds_bpermute_b32 v33, v155, v32
	s_waitcnt lgkmcnt(0)
	v_add_f32_e32 v32, v32, v33
	v_fmamk_f32 v32, v32, 0x3c800000, v218
	v_cmp_gt_f32_e32 vcc, s3, v32
	v_mul_f32_e32 v33, 0x4f800000, v32
	s_nop 0
	v_cndmask_b32_e32 v32, v32, v33, vcc
	v_sqrt_f32_e32 v33, v32
	s_nop 0
	v_add_u32_e32 v34, -1, v33
	v_fma_f32 v35, -v34, v33, v32
	v_cmp_ge_f32_e64 s[0:1], 0, v35
	v_add_u32_e32 v35, 1, v33
	s_nop 0
	v_cndmask_b32_e64 v34, v33, v34, s[0:1]
	v_fma_f32 v33, -v35, v33, v32
	v_cmp_lt_f32_e64 s[0:1], 0, v33
	s_nop 1
	v_cndmask_b32_e64 v33, v34, v35, s[0:1]
	v_mul_f32_e32 v34, 0x37800000, v33
	v_cndmask_b32_e32 v33, v33, v34, vcc
	v_cmp_class_f32_e32 vcc, v32, v219
	s_nop 1
	v_cndmask_b32_e32 v32, v33, v32, vcc
	v_div_scale_f32 v33, s[0:1], v32, v32, 1.0
	v_rcp_f32_e32 v34, v33
	s_nop 0
	v_fma_f32 v35, -v33, v34, 1.0
	v_fmac_f32_e32 v34, v35, v34
	v_div_scale_f32 v35, vcc, 1.0, v32, 1.0
	v_mul_f32_e32 v36, v35, v34
	v_fma_f32 v37, -v33, v36, v35
	v_fmac_f32_e32 v36, v37, v34
	v_fma_f32 v33, -v33, v36, v35
	v_div_fmas_f32 v33, v33, v34, v36
	v_div_fixup_f32 v52, v33, v32, 1.0
	v_lshlrev_b64 v[32:33], 9, v[54:55]
	v_lshl_add_u64 v[56:57], s[14:15], 0, v[32:33]
	v_lshlrev_b64 v[32:33], 10, v[54:55]
	v_lshl_add_u64 v[54:55], s[24:25], 0, v[32:33]
	global_load_dwordx4 v[32:35], v184, s[40:41] offset:16
	global_load_dwordx4 v[36:39], v184, s[40:41]
	v_pk_mul_f32 v[60:61], v[60:61], v[52:53] op_sel_hi:[1,0]
	v_pk_mul_f32 v[58:59], v[58:59], v[52:53] op_sel_hi:[1,0]
	v_pk_mul_f32 v[40:41], v[40:41], v[52:53] op_sel_hi:[1,0]
	v_pk_mul_f32 v[42:43], v[42:43], v[52:53] op_sel_hi:[1,0]
	v_lshl_add_u64 v[56:57], v[56:57], 0, v[124:125]
	v_lshl_add_u64 v[54:55], v[54:55], 0, v[184:185]
	s_waitcnt vmcnt(1)
	v_pk_mul_f32 v[34:35], v[34:35], v[42:43]
	s_waitcnt vmcnt(0)
	v_pk_mul_f32 v[38:39], v[38:39], v[58:59]
	v_pk_mul_f32 v[36:37], v[36:37], v[60:61]
	v_pk_mul_f32 v[32:33], v[32:33], v[40:41]
	v_cvt_pk_bf16_f32 v40, v36, v37
	v_cvt_pk_bf16_f32 v41, v38, v39
	s_nop 0
	v_cvt_pk_bf16_f32 v42, v32, v33
	v_cvt_pk_bf16_f32 v43, v34, v35
	global_store_dwordx4 v[56:57], v[40:43], off
	global_store_dwordx4 v[54:55], v[36:39], off nt
	global_store_dwordx4 v[54:55], v[32:35], off offset:16 nt
	global_load_dwordx4 v[32:35], v169, s[40:41] offset:16
	s_nop 0
	global_load_dwordx4 v[36:39], v169, s[40:41]
	v_pk_mul_f32 v[40:41], v[50:51], v[52:53] op_sel_hi:[1,0]
	v_pk_mul_f32 v[42:43], v[46:47], v[52:53] op_sel_hi:[1,0]
	s_waitcnt vmcnt(0)
; __device__ __forceinline__ float quad_sum(float s) { s += __shfl_xor(s, 16); s += __shfl_xor(s, 32); return s; }
; __device__ __forceinline__ float sq4(const f32x4 a) { return (a[0] * a[0] + a[1] * a[1]) + (a[2] * a[2] + a[3] * a[3]); }
; __device__ __forceinline__ u32x4 pack8(const f32x4 a, const f32x4 b) { u32x4 w; w.x = cvt_pk_bf16(a[0], a[1]); w.y = cvt_pk_bf16(a[2], a[3]); w.z = cvt_pk_bf16(b[0], b[1]); w.w = cvt_pk_bf16(b[2], b[3]); return w; }
;     __device__ __forceinline__ void operator()(const f32x4 (&acc)[2][2][4][2], const Unit& u, int wr, int wc, int fr, int fq) const {
;     ...
;                     int mrow = ai * HALF + wr * 64 + m * 16 + fr;
;                     asm volatile("" : "+v"(mrow));
;                     const float rs = MRS[b * 256 + mrow];
;                     f32x4 v[2][2];
; #pragma unroll
;                     for (int bj = 0; bj < 2; ++bj)
; #pragma unroll
;                         for (int n = 0; n < 2; ++n) v[bj][n] = acc[ai][bj][m][n] * rs;
;                     float ss = (sq4(v[0][0]) + sq4(v[0][1])) + (sq4(v[1][0]) + sq4(v[1][1]));
;                     ss = quad_sum(ss);
;                     const float hr = 1.0f / sqrtf(ss * (1.0f / 64.0f) + E_EPS);
; #pragma unroll
;                     for (int bj = 0; bj < 2; ++bj) {
;                         const int c0 = bj * 32 + 8 * fq;
;                         const f32x4 g0 = *(const f32x4*)(g + c0), g1 = *(const f32x4*)(g + c0 + 4);
;                         const f32x4 o0 = v[bj][0] * hr * g0, o1 = v[bj][1] * hr * g1;
;                         *(u32x4*)(MK + ((size_t)(l * 40 + b) * 256 + mrow) * 256 + wc * 64 + c0) = pack8(o0, o1);
;                         float* d = o_mk + ((size_t)(l * 8 + b) * 256 + mrow) * 256 + wc * 64 + c0; __builtin_nontemporal_store(o0, (f32x4*)d); __builtin_nontemporal_store(o1, (f32x4*)(d + 4));
;                     }
	v_pk_mul_f32 v[36:37], v[36:37], v[40:41]
	v_pk_mul_f32 v[38:39], v[38:39], v[42:43]
	v_pk_mul_f32 v[40:41], v[48:49], v[52:53] op_sel_hi:[1,0]
	v_pk_mul_f32 v[42:43], v[44:45], v[52:53] op_sel_hi:[1,0]
	v_pk_mul_f32 v[32:33], v[32:33], v[40:41]
	v_pk_mul_f32 v[34:35], v[34:35], v[42:43]
	v_cvt_pk_bf16_f32 v40, v36, v37
	v_cvt_pk_bf16_f32 v41, v38, v39
	v_cvt_pk_bf16_f32 v42, v32, v33
	s_nop 0
	v_cvt_pk_bf16_f32 v43, v34, v35
	global_store_dwordx4 v[56:57], v[40:43], off offset:64
	global_store_dwordx4 v[54:55], v[36:39], off offset:128 nt
	global_store_dwordx4 v[54:55], v[32:35], off offset:144 nt
	s_nop 0
	v_mov_b32_e32 v38, v166
	s_nop 0
	v_mov_b32_e32 v32, v226
	v_ashrrev_i32_e32 v39, 31, v38
	v_pk_mul_f32 v[44:45], v[28:29], v[32:33] op_sel_hi:[1,0]
	v_pk_mul_f32 v[34:35], v[20:21], v[32:33] op_sel_hi:[1,0]
	v_pk_mul_f32 v[42:43], v[30:31], v[32:33] op_sel_hi:[1,0]
	v_pk_mul_f32 v[30:31], v[22:23], v[32:33] op_sel_hi:[1,0]
	v_pk_mul_f32 v[28:29], v[18:19], v[32:33] op_sel_hi:[1,0]
	v_mov_b32_e32 v18, v45
	v_mov_b32_e32 v19, v35
	v_pk_mul_f32 v[26:27], v[26:27], v[32:33] op_sel_hi:[1,0]
	v_pk_mul_f32 v[24:25], v[24:25], v[32:33] op_sel_hi:[1,0]
	v_pk_mul_f32 v[32:33], v[16:17], v[32:33] op_sel_hi:[1,0]
	v_mov_b32_e32 v16, v44
	v_mov_b32_e32 v17, v34
	v_pk_mul_f32 v[18:19], v[18:19], v[18:19]
	v_mov_b32_e32 v20, v43
	v_mov_b32_e32 v21, v31
	v_pk_fma_f32 v[16:17], v[16:17], v[16:17], v[18:19]
	v_mov_b32_e32 v18, v42
	v_mov_b32_e32 v19, v30
	v_pk_mul_f32 v[20:21], v[20:21], v[20:21]
	v_mov_b32_e32 v22, v27
	v_pk_fma_f32 v[18:19], v[18:19], v[18:19], v[20:21]
	v_mov_b32_e32 v20, v25
	v_mov_b32_e32 v21, v33
	v_pk_add_f32 v[16:17], v[16:17], v[18:19]
	v_mov_b32_e32 v18, v24
	v_mov_b32_e32 v19, v32
	v_pk_mul_f32 v[20:21], v[20:21], v[20:21]
	v_mov_b32_e32 v23, v29
	v_pk_fma_f32 v[18:19], v[18:19], v[18:19], v[20:21]
	v_mov_b32_e32 v20, v26
	v_mov_b32_e32 v21, v28
	v_pk_mul_f32 v[22:23], v[22:23], v[22:23]
	s_nop 0
	v_pk_fma_f32 v[20:21], v[20:21], v[20:21], v[22:23]
	s_nop 0
	v_pk_add_f32 v[18:19], v[18:19], v[20:21]
	s_nop 0
	v_pk_add_f32 v[16:17], v[16:17], v[18:19]
	s_nop 0
	v_add_f32_e32 v16, v16, v17
	ds_bpermute_b32 v17, v135, v16
	s_waitcnt lgkmcnt(0)
	v_add_f32_e32 v16, v16, v17
	ds_bpermute_b32 v17, v155, v16
	s_waitcnt lgkmcnt(0)
	v_add_f32_e32 v16, v16, v17
	v_fmamk_f32 v16, v16, 0x3c800000, v218
	v_cmp_gt_f32_e32 vcc, s3, v16
	v_mul_f32_e32 v17, 0x4f800000, v16
	s_nop 0
	v_cndmask_b32_e32 v16, v16, v17, vcc
	v_sqrt_f32_e32 v17, v16
	s_nop 0
	v_add_u32_e32 v18, -1, v17
	v_fma_f32 v19, -v18, v17, v16
	v_cmp_ge_f32_e64 s[0:1], 0, v19
	v_add_u32_e32 v19, 1, v17
	s_nop 0
	v_cndmask_b32_e64 v18, v17, v18, s[0:1]
	v_fma_f32 v17, -v19, v17, v16
	v_cmp_lt_f32_e64 s[0:1], 0, v17
	s_nop 1
	v_cndmask_b32_e64 v17, v18, v19, s[0:1]
	v_mul_f32_e32 v18, 0x37800000, v17
	v_cndmask_b32_e32 v17, v17, v18, vcc
	v_cmp_class_f32_e32 vcc, v16, v219
	s_nop 1
	v_cndmask_b32_e32 v16, v17, v16, vcc
	v_div_scale_f32 v17, s[0:1], v16, v16, 1.0
	v_rcp_f32_e32 v18, v17
	s_nop 0
	v_fma_f32 v19, -v17, v18, 1.0
	v_fmac_f32_e32 v18, v19, v18
	v_div_scale_f32 v19, vcc, 1.0, v16, 1.0
	v_mul_f32_e32 v20, v19, v18
	v_fma_f32 v21, -v17, v20, v19
	v_fmac_f32_e32 v20, v21, v18
	v_fma_f32 v17, -v17, v20, v19
	v_div_fmas_f32 v17, v17, v18, v20
	v_div_fixup_f32 v36, v17, v16, 1.0
	v_lshlrev_b64 v[16:17], 9, v[38:39]
	v_lshl_add_u64 v[40:41], s[14:15], 0, v[16:17]
	v_lshlrev_b64 v[16:17], 10, v[38:39]
	v_lshl_add_u64 v[38:39], s[24:25], 0, v[16:17]
	global_load_dwordx4 v[16:19], v184, s[40:41] offset:16
	global_load_dwordx4 v[20:23], v184, s[40:41]
	v_pk_mul_f32 v[44:45], v[44:45], v[36:37] op_sel_hi:[1,0]
	v_pk_mul_f32 v[42:43], v[42:43], v[36:37] op_sel_hi:[1,0]
	v_pk_mul_f32 v[24:25], v[24:25], v[36:37] op_sel_hi:[1,0]
	v_pk_mul_f32 v[26:27], v[26:27], v[36:37] op_sel_hi:[1,0]
	v_lshl_add_u64 v[40:41], v[40:41], 0, v[124:125]
	v_lshl_add_u64 v[38:39], v[38:39], 0, v[184:185]
	s_waitcnt vmcnt(1)
	v_pk_mul_f32 v[18:19], v[18:19], v[26:27]
	s_waitcnt vmcnt(0)
	v_pk_mul_f32 v[22:23], v[22:23], v[42:43]
	v_pk_mul_f32 v[20:21], v[20:21], v[44:45]
	v_pk_mul_f32 v[16:17], v[16:17], v[24:25]
	v_cvt_pk_bf16_f32 v24, v20, v21
	v_cvt_pk_bf16_f32 v25, v22, v23
	s_nop 0
	v_cvt_pk_bf16_f32 v26, v16, v17
	v_cvt_pk_bf16_f32 v27, v18, v19
	global_store_dwordx4 v[40:41], v[24:27], off
	global_store_dwordx4 v[38:39], v[20:23], off nt
	global_store_dwordx4 v[38:39], v[16:19], off offset:16 nt
	global_load_dwordx4 v[16:19], v169, s[40:41] offset:16
	s_nop 0
	global_load_dwordx4 v[20:23], v169, s[40:41]
	v_pk_mul_f32 v[24:25], v[34:35], v[36:37] op_sel_hi:[1,0]
	v_pk_mul_f32 v[26:27], v[30:31], v[36:37] op_sel_hi:[1,0]
	s_waitcnt vmcnt(0)
; __device__ __forceinline__ float quad_sum(float s) { s += __shfl_xor(s, 16); s += __shfl_xor(s, 32); return s; }
; __device__ __forceinline__ float sq4(const f32x4 a) { return (a[0] * a[0] + a[1] * a[1]) + (a[2] * a[2] + a[3] * a[3]); }
; __device__ __forceinline__ u32x4 pack8(const f32x4 a, const f32x4 b) { u32x4 w; w.x = cvt_pk_bf16(a[0], a[1]); w.y = cvt_pk_bf16(a[2], a[3]); w.z = cvt_pk_bf16(b[0], b[1]); w.w = cvt_pk_bf16(b[2], b[3]); return w; }
;     __device__ __forceinline__ void operator()(const f32x4 (&acc)[2][2][4][2], const Unit& u, int wr, int wc, int fr, int fq) const {
;     ...
;                     int mrow = ai * HALF + wr * 64 + m * 16 + fr;
;                     asm volatile("" : "+v"(mrow));
;                     const float rs = MRS[b * 256 + mrow];
;                     f32x4 v[2][2];
; #pragma unroll
;                     for (int bj = 0; bj < 2; ++bj)
; #pragma unroll
;                         for (int n = 0; n < 2; ++n) v[bj][n] = acc[ai][bj][m][n] * rs;
;                     float ss = (sq4(v[0][0]) + sq4(v[0][1])) + (sq4(v[1][0]) + sq4(v[1][1]));
;                     ss = quad_sum(ss);
;                     const float hr = 1.0f / sqrtf(ss * (1.0f / 64.0f) + E_EPS);
; #pragma unroll
;                     for (int bj = 0; bj < 2; ++bj) {
;                         const int c0 = bj * 32 + 8 * fq;
;                         const f32x4 g0 = *(const f32x4*)(g + c0), g1 = *(const f32x4*)(g + c0 + 4);
;                         const f32x4 o0 = v[bj][0] * hr * g0, o1 = v[bj][1] * hr * g1;
;                         *(u32x4*)(MK + ((size_t)(l * 40 + b) * 256 + mrow) * 256 + wc * 64 + c0) = pack8(o0, o1);
;                         float* d = o_mk + ((size_t)(l * 8 + b) * 256 + mrow) * 256 + wc * 64 + c0; __builtin_nontemporal_store(o0, (f32x4*)d); __builtin_nontemporal_store(o1, (f32x4*)(d + 4));
;                     }
	v_pk_mul_f32 v[20:21], v[20:21], v[24:25]
	v_pk_mul_f32 v[22:23], v[22:23], v[26:27]
	v_pk_mul_f32 v[24:25], v[32:33], v[36:37] op_sel_hi:[1,0]
	v_pk_mul_f32 v[26:27], v[28:29], v[36:37] op_sel_hi:[1,0]
	v_pk_mul_f32 v[16:17], v[16:17], v[24:25]
	v_pk_mul_f32 v[18:19], v[18:19], v[26:27]
	v_cvt_pk_bf16_f32 v24, v20, v21
	v_cvt_pk_bf16_f32 v25, v22, v23
	v_cvt_pk_bf16_f32 v26, v16, v17
	s_nop 0
	v_cvt_pk_bf16_f32 v27, v18, v19
	global_store_dwordx4 v[40:41], v[24:27], off offset:64
	global_store_dwordx4 v[38:39], v[20:23], off offset:128 nt
	global_store_dwordx4 v[38:39], v[16:19], off offset:144 nt
	s_nop 0
	v_mov_b32_e32 v22, v167
	s_nop 0
	v_mov_b32_e32 v16, v250
	v_ashrrev_i32_e32 v23, 31, v22
	v_pk_mul_f32 v[28:29], v[12:13], v[16:17] op_sel_hi:[1,0]
	v_pk_mul_f32 v[18:19], v[4:5], v[16:17] op_sel_hi:[1,0]
	v_pk_mul_f32 v[26:27], v[14:15], v[16:17] op_sel_hi:[1,0]
	v_pk_mul_f32 v[14:15], v[6:7], v[16:17] op_sel_hi:[1,0]
	v_pk_mul_f32 v[12:13], v[2:3], v[16:17] op_sel_hi:[1,0]
	v_mov_b32_e32 v2, v29
	v_mov_b32_e32 v3, v19
	v_pk_mul_f32 v[10:11], v[10:11], v[16:17] op_sel_hi:[1,0]
	v_pk_mul_f32 v[8:9], v[8:9], v[16:17] op_sel_hi:[1,0]
	v_pk_mul_f32 v[16:17], v[0:1], v[16:17] op_sel_hi:[1,0]
	v_mov_b32_e32 v0, v28
	v_mov_b32_e32 v1, v18
	v_pk_mul_f32 v[2:3], v[2:3], v[2:3]
	v_mov_b32_e32 v4, v27
	v_mov_b32_e32 v5, v15
	v_pk_fma_f32 v[0:1], v[0:1], v[0:1], v[2:3]
	v_mov_b32_e32 v2, v26
	v_mov_b32_e32 v3, v14
	v_pk_mul_f32 v[4:5], v[4:5], v[4:5]
	v_mov_b32_e32 v6, v11
	v_pk_fma_f32 v[2:3], v[2:3], v[2:3], v[4:5]
	v_mov_b32_e32 v4, v9
	v_mov_b32_e32 v5, v17
	v_pk_add_f32 v[0:1], v[0:1], v[2:3]
	v_mov_b32_e32 v2, v8
	v_mov_b32_e32 v3, v16
	v_pk_mul_f32 v[4:5], v[4:5], v[4:5]
	v_mov_b32_e32 v7, v13
	v_pk_fma_f32 v[2:3], v[2:3], v[2:3], v[4:5]
	v_mov_b32_e32 v4, v10
	v_mov_b32_e32 v5, v12
	v_pk_mul_f32 v[6:7], v[6:7], v[6:7]
	s_nop 0
	v_pk_fma_f32 v[4:5], v[4:5], v[4:5], v[6:7]
	s_nop 0
	v_pk_add_f32 v[2:3], v[2:3], v[4:5]
	s_nop 0
	v_pk_add_f32 v[0:1], v[0:1], v[2:3]
	s_nop 0
	v_add_f32_e32 v0, v0, v1
	ds_bpermute_b32 v1, v135, v0
	s_waitcnt lgkmcnt(0)
	v_add_f32_e32 v0, v0, v1
	ds_bpermute_b32 v1, v155, v0
	s_waitcnt lgkmcnt(0)
	v_add_f32_e32 v0, v0, v1
	v_fmamk_f32 v0, v0, 0x3c800000, v218
	v_cmp_gt_f32_e32 vcc, s3, v0
	v_mul_f32_e32 v1, 0x4f800000, v0
	s_nop 0
	v_cndmask_b32_e32 v0, v0, v1, vcc
	v_sqrt_f32_e32 v1, v0
	s_nop 0
	v_add_u32_e32 v2, -1, v1
	v_fma_f32 v3, -v2, v1, v0
	v_cmp_ge_f32_e64 s[0:1], 0, v3
	v_add_u32_e32 v3, 1, v1
	s_nop 0
	v_cndmask_b32_e64 v2, v1, v2, s[0:1]
	v_fma_f32 v1, -v3, v1, v0
	v_cmp_lt_f32_e64 s[0:1], 0, v1
	s_nop 1
	v_cndmask_b32_e64 v1, v2, v3, s[0:1]
	v_mul_f32_e32 v2, 0x37800000, v1
	v_cndmask_b32_e32 v1, v1, v2, vcc
	v_cmp_class_f32_e32 vcc, v0, v219
	s_nop 1
	v_cndmask_b32_e32 v0, v1, v0, vcc
	v_div_scale_f32 v1, s[0:1], v0, v0, 1.0
	v_rcp_f32_e32 v2, v1
	s_nop 0
	v_fma_f32 v3, -v1, v2, 1.0
	v_fmac_f32_e32 v2, v3, v2
	v_div_scale_f32 v3, vcc, 1.0, v0, 1.0
	v_mul_f32_e32 v4, v3, v2
	v_fma_f32 v5, -v1, v4, v3
	v_fmac_f32_e32 v4, v5, v2
	v_fma_f32 v1, -v1, v4, v3
	v_div_fmas_f32 v1, v1, v2, v4
	v_div_fixup_f32 v20, v1, v0, 1.0
	v_lshlrev_b64 v[0:1], 9, v[22:23]
	v_lshl_add_u64 v[24:25], s[14:15], 0, v[0:1]
	v_lshlrev_b64 v[0:1], 10, v[22:23]
	v_lshl_add_u64 v[22:23], s[24:25], 0, v[0:1]
	global_load_dwordx4 v[0:3], v184, s[40:41] offset:16
	global_load_dwordx4 v[4:7], v184, s[40:41]
	v_pk_mul_f32 v[28:29], v[28:29], v[20:21] op_sel_hi:[1,0]
	v_pk_mul_f32 v[26:27], v[26:27], v[20:21] op_sel_hi:[1,0]
	v_pk_mul_f32 v[8:9], v[8:9], v[20:21] op_sel_hi:[1,0]
	v_pk_mul_f32 v[10:11], v[10:11], v[20:21] op_sel_hi:[1,0]
	v_lshl_add_u64 v[24:25], v[24:25], 0, v[124:125]
	v_pk_mul_f32 v[14:15], v[14:15], v[20:21] op_sel_hi:[1,0]
	v_pk_mul_f32 v[12:13], v[12:13], v[20:21] op_sel_hi:[1,0]
	s_waitcnt vmcnt(1)
	v_pk_mul_f32 v[0:1], v[0:1], v[8:9]
	s_waitcnt vmcnt(0)
	v_pk_mul_f32 v[6:7], v[6:7], v[26:27]
	v_pk_mul_f32 v[4:5], v[4:5], v[28:29]
	v_pk_mul_f32 v[2:3], v[2:3], v[10:11]
	v_cvt_pk_bf16_f32 v8, v4, v5
	v_cvt_pk_bf16_f32 v9, v6, v7
	v_cvt_pk_bf16_f32 v10, v0, v1
	s_nop 0
	v_cvt_pk_bf16_f32 v11, v2, v3
	global_store_dwordx4 v[24:25], v[8:11], off
	s_nop 1
	v_lshl_add_u64 v[8:9], v[22:23], 0, v[184:185]
	global_store_dwordx4 v[8:9], v[4:7], off nt
	global_store_dwordx4 v[8:9], v[0:3], off offset:16 nt
	global_load_dwordx4 v[0:3], v169, s[40:41] offset:16
	s_nop 0
	global_load_dwordx4 v[4:7], v169, s[40:41]
	v_pk_mul_f32 v[10:11], v[18:19], v[20:21] op_sel_hi:[1,0]
	v_lshl_add_u64 v[156:157], v[8:9], 0, s[96:97]
	s_waitcnt vmcnt(1)
	v_pk_mul_f32 v[130:131], v[2:3], v[12:13]
	s_waitcnt vmcnt(0)
	v_pk_mul_f32 v[4:5], v[4:5], v[10:11]
	v_pk_mul_f32 v[10:11], v[16:17], v[20:21] op_sel_hi:[1,0]
	v_pk_mul_f32 v[6:7], v[6:7], v[14:15]
	v_pk_mul_f32 v[128:129], v[0:1], v[10:11]
	v_cvt_pk_bf16_f32 v0, v4, v5
	v_cvt_pk_bf16_f32 v1, v6, v7
	s_nop 0
	v_cvt_pk_bf16_f32 v2, v128, v129
	v_cvt_pk_bf16_f32 v3, v130, v131
	global_store_dwordx4 v[24:25], v[0:3], off offset:64
	global_store_dwordx4 v[8:9], v[4:7], off offset:128 nt
	s_andn2_b64 vcc, exec, s[36:37]
	s_mov_b64 s[0:1], -1
	global_store_dwordx4 v[156:157], v[128:131], off offset:16 nt
	s_cbranch_vccnz .LBB0_501
